# ssm_p1 end states via per-lane weighted sums (no serial scan, no cross-lane swaps)
# speedup vs baseline: 1.0122x; 1.0122x over previous
; #define WSPTR() kptr(224)
; template <bool BWD, int MODE  >
; __device__ __forceinline__ void ssm_pass(const bf16* proj, int rowbase, int g, const bf16x8* BBp, const bf16x8* CCp, float ar, float ai, float& sr, float& si,
;                                          LAS unsigned* XS, int lane, f32x4* ysc, const float* Dp, bf16* zbuf) {
;     bf16x8 bb[4], cc[4];
; #pragma unroll
;     for (int t = 0; t < 4; ++t) { bb[t] = BBp[t * 64 + lane]; if (MODE > 0) cc[t] = CCp[t * 64 + lane]; }
;     const int ql = lane & 31, hi = lane >> 5;
;     const bf16* up = proj + (size_t)(rowbase + ql) * DIN + 768 + g * 16 + 8 * hi;
;     bf16x8 ucur = *(const bf16x8*)(up + (size_t)(BWD ? 15 : 0) * 32 * DIN);
;     float dval = 0.f; if (MODE == 2) dval = Dp[g * 16 + (lane & 15)];
; __device__ __forceinline__ void ssm_p1(const Args& a, LAS unsigned char* lds, int layer, int G, int vb) {
;     ...
;         const int b = (wt >> 3) & 7, tl = (wt >> 6) * 8 + (wt & 7), dir = tl & 1, seg = (tl >> 1) & 7, g = (tl >> 4) & 31;
;         const int cb = (layer * 2 + dir) * 32 + g;
;         const f32x2 ab = AB[cb * 64 + lane];
;         float sr = 0.f, si = 0.f;
;         const bf16x8* BBp = (const bf16x8*)(WSPTR() + WS_BB) + (size_t)cb * 4 * 64;
;         const int rowbase = b * SEQ + seg * 512;
;         if (dir) ssm_pass<true, 0>(proj, rowbase, g, BBp, nullptr, ab[0], ab[1], sr, si, XS, lane, nullptr, nullptr, nullptr);
.LBB0_438:
	s_bfe_u32 s27, s18, 0x50007
	s_lshr_b32 s22, s18, 3
	s_or_b32 s28, s27, s26
	s_and_b32 s22, s22, 8
	s_and_b32 s23, s18, 6
	v_lshl_or_b32 v0, s28, 6, v87
	s_or_b32 s36, s22, s23
	v_lshl_add_u64 v[2:3], v[0:1], 3, s[6:7]
	s_movk_i32 s22, 0xe0
	s_lshl_b32 s52, s27, 5
	s_bfe_u32 s37, s18, 0x30003
	global_load_dwordx2 v[98:99], v[2:3], off
	global_load_dwordx2 v[130:131], v[2:3], off offset:256
	s_ashr_i32 s23, s22, 31
	s_add_u32 s22, s0, s22
	s_addc_u32 s23, s1, s23
	s_load_dwordx2 s[22:23], s[22:23], 0x0
	s_lshl_b32 s28, s28, 12
	v_mov_b32_e32 v93, v1
	v_mov_b32_e32 v95, v1
	s_waitcnt lgkmcnt(0)
	s_add_u32 s22, s22, s28
	s_addc_u32 s23, s23, 0
	v_lshl_add_u64 v[2:3], s[22:23], 0, v[92:93]
	v_lshl_add_u64 v[4:5], v[2:3], 0, s[66:67]
	v_add_co_u32_e32 v2, vcc, s46, v2
	s_lshl_b32 s22, s37, 12
	s_nop 0
	v_addc_co_u32_e32 v3, vcc, 0, v3, vcc
	global_load_dwordx4 v[66:69], v[4:5], off offset:1024
	global_load_dwordx4 v[70:73], v[4:5], off offset:2048
	global_load_dwordx4 v[74:77], v[2:3], off
	global_load_dwordx4 v[78:81], v[4:5], off offset:3072
	s_lshl_b32 s23, s36, 8
	s_or_b32 s22, s23, s22
	v_or_b32_e32 v0, s22, v87
	v_mul_u32_u24_e32 v0, 0x500, v0
	v_lshlrev_b32_e32 v2, 1, v0
	v_mov_b32_e32 v3, v1
	v_lshl_add_u64 v[2:3], s[4:5], 0, v[2:3]
	v_lshl_add_u64 v[2:3], v[2:3], 0, s[52:53]
	v_lshl_add_u64 v[2:3], v[2:3], 0, v[94:95]
	s_mov_b64 s[22:23], 0xd800600
	v_lshl_add_u64 v[102:103], v[2:3], 0, s[22:23]
	s_mov_b64 s[22:23], -1
	s_andn2_b64 vcc, exec, s[76:77]
	v_lshl_add_u64 v[100:101], v[0:1], 1, s[52:53]
	s_waitcnt vmcnt(4)
	v_xor_b32_e32 v96, 0x80000000, v99
	s_cbranch_vccnz .LBB0_444
	v_add_co_u32_e32 v2, vcc, 0x12c000, v102
	s_nop 1
	v_addc_co_u32_e32 v3, vcc, 0, v103, vcc
	global_load_dwordx4 v[114:117], v[2:3], off
	v_lshl_add_u64 v[108:109], v[88:89], 0, v[100:101]
	global_load_dwordx4 v[118:121], v[108:109], off
	v_lshl_add_u64 v[108:109], v[108:109], 0, s[68:69]
	global_load_dwordx4 v[122:125], v[108:109], off
	v_lshl_add_u64 v[108:109], v[108:109], 0, s[68:69]
	v_cmp_lt_u32_e32 vcc, 31, v86
	s_nop 1
	v_mul_f32_e32 v215, v98, v98
	v_fma_f32 v215, -v99, v99, v215
	v_mul_f32_e32 v216, v98, v99
	v_fmac_f32_e32 v216, v99, v98
	v_mul_f32_e32 v217, v215, v215
	v_fma_f32 v217, -v216, v216, v217
	v_mul_f32_e32 v194, v215, v216
	v_fmac_f32_e32 v194, v216, v215
	v_mul_f32_e32 v195, v217, v217
	v_fma_f32 v195, -v194, v194, v195
	v_mul_f32_e32 v196, v217, v194
	v_fmac_f32_e32 v196, v194, v217
	v_mul_f32_e32 v197, v195, v195
	v_fma_f32 v197, -v196, v196, v197
	v_mul_f32_e32 v198, v195, v196
	v_fmac_f32_e32 v198, v196, v195
	v_mul_f32_e32 v199, v197, v195
	v_fma_f32 v199, -v198, v196, v199
	v_mul_f32_e32 v200, v197, v196
	v_fmac_f32_e32 v200, v198, v195
	v_mul_f32_e32 v159, v197, v197
	v_fma_f32 v159, -v198, v198, v159
	v_mul_f32_e32 v160, v197, v198
	v_fmac_f32_e32 v160, v198, v197
	v_mov_b32_e32 v201, 1.0
	v_mov_b32_e32 v202, 0
	v_cndmask_b32_e32 v201, v201, v217, vcc
	v_cndmask_b32_e32 v202, v202, v194, vcc
	v_mul_f32_e32 v203, v201, v98
	v_fma_f32 v203, -v202, v99, v203
	v_mul_f32_e32 v204, v201, v99
	v_fmac_f32_e32 v204, v202, v98
	v_mul_f32_e32 v205, v201, v215
	v_fma_f32 v205, -v202, v216, v205
	v_mul_f32_e32 v206, v201, v216
	v_fmac_f32_e32 v206, v202, v215
	v_mul_f32_e32 v207, v205, v98
	v_fma_f32 v207, -v206, v99, v207
	v_mul_f32_e32 v208, v205, v99
	v_fmac_f32_e32 v208, v206, v98
	v_mov_b32_e32 v178, v201
	v_mov_b32_e32 v226, v202
	v_mov_b32_e32 v179, v203
	v_mov_b32_e32 v227, v204
	v_mov_b32_e32 v180, v205
	v_mov_b32_e32 v228, v206
	v_mov_b32_e32 v181, v207
	v_mov_b32_e32 v229, v208
	v_mul_f32_e32 v182, v201, v195
	v_fma_f32 v182, -v202, v196, v182
	v_mul_f32_e32 v230, v201, v196
	v_fmac_f32_e32 v230, v202, v195
	v_mul_f32_e32 v183, v203, v195
	v_fma_f32 v183, -v204, v196, v183
	v_mul_f32_e32 v231, v203, v196
	v_fmac_f32_e32 v231, v204, v195
	v_mul_f32_e32 v184, v205, v195
	v_fma_f32 v184, -v206, v196, v184
	v_mul_f32_e32 v232, v205, v196
	v_fmac_f32_e32 v232, v206, v195
	v_mul_f32_e32 v185, v207, v195
	v_fma_f32 v185, -v208, v196, v185
	v_mul_f32_e32 v233, v207, v196
	v_fmac_f32_e32 v233, v208, v195
	v_mul_f32_e32 v186, v201, v197
	v_fma_f32 v186, -v202, v198, v186
	v_mul_f32_e32 v234, v201, v198
	v_fmac_f32_e32 v234, v202, v197
	v_mul_f32_e32 v187, v203, v197
	v_fma_f32 v187, -v204, v198, v187
	v_mul_f32_e32 v235, v203, v198
	v_fmac_f32_e32 v235, v204, v197
	v_mul_f32_e32 v188, v205, v197
	v_fma_f32 v188, -v206, v198, v188
	v_mul_f32_e32 v236, v205, v198
	v_fmac_f32_e32 v236, v206, v197
	v_mul_f32_e32 v189, v207, v197
	v_fma_f32 v189, -v208, v198, v189
	v_mul_f32_e32 v237, v207, v198
	v_fmac_f32_e32 v237, v208, v197
	v_mul_f32_e32 v190, v201, v199
	v_fma_f32 v190, -v202, v200, v190
	v_mul_f32_e32 v238, v201, v200
	v_fmac_f32_e32 v238, v202, v199
	v_mul_f32_e32 v191, v203, v199
	v_fma_f32 v191, -v204, v200, v191
	v_mul_f32_e32 v239, v203, v200
	v_fmac_f32_e32 v239, v204, v199
	v_mul_f32_e32 v192, v205, v199
	v_fma_f32 v192, -v206, v200, v192
	v_mul_f32_e32 v240, v205, v200
	v_fmac_f32_e32 v240, v206, v199
	v_mul_f32_e32 v193, v207, v199
	v_fma_f32 v193, -v208, v200, v193
	v_mul_f32_e32 v241, v207, v200
	v_fmac_f32_e32 v241, v208, v199
	v_mul_f32_e32 v215, v130, v130
	v_fma_f32 v215, -v131, v131, v215
	v_mul_f32_e32 v216, v130, v131
	v_fmac_f32_e32 v216, v131, v130
	v_mul_f32_e32 v217, v215, v215
	v_fma_f32 v217, -v216, v216, v217
	v_mul_f32_e32 v194, v215, v216
	v_fmac_f32_e32 v194, v216, v215
	v_mul_f32_e32 v195, v217, v217
	v_fma_f32 v195, -v194, v194, v195
	v_mul_f32_e32 v196, v217, v194
	v_fmac_f32_e32 v196, v194, v217
	v_mul_f32_e32 v197, v195, v195
	v_fma_f32 v197, -v196, v196, v197
	v_mul_f32_e32 v198, v195, v196
; __device__ __forceinline__ unsigned pk2(float lo, float hi) { const f32x2 v = {lo, hi}; return __builtin_bit_cast(unsigned, __builtin_convertvector(v, bf16x2_t)); }
; __device__ __forceinline__ float bflo(unsigned w) { return __uint_as_float(w << 16); }
; __device__ __forceinline__ float bfhi(unsigned w) { return __uint_as_float(w & 0xffff0000u); }
; #define LDS_FENCE() asm volatile("s_waitcnt lgkmcnt(0)" ::: "memory")
; template <bool BWD, int MODE  >
; __device__ __forceinline__ void ssm_pass(const bf16* proj, int rowbase, int g, const bf16x8* BBp, const bf16x8* CCp, float ar, float ai, float& sr, float& si,
;                                          LAS unsigned* XS, int lane, f32x4* ysc, const float* Dp, bf16* zbuf) {
;     ...
;     for (int c = 0; c < 16; ++c) {
;         const int ch = BWD ? 15 - c : c;
;         bf16x8 unext = ucur;
;         if (c < 15) unext = *(const bf16x8*)(up + (size_t)(BWD ? ch - 1 : ch + 1) * 32 * DIN);
;         f32x4 y0 = (f32x4){0.f, 0.f, 0.f, 0.f}, y1 = y0; bf16 uvl[8];
;         if (MODE == 2) {
;             y0 = ysc[(ch * 2 + 0) * 64 + lane]; y1 = ysc[(ch * 2 + 1) * 64 + lane];
; #pragma unroll
;             for (int q = 0; q < 8; ++q) uvl[q] = proj[(size_t)(rowbase + 32 * ch + 16 * (q >> 2) + 4 * (lane >> 4) + (q & 3)) * DIN + 768 + g * 16 + (lane & 15)];
;         }
;         f32x16 z16;
; #pragma unroll
;         for (int r = 0; r < 16; ++r) z16[r] = 0.f;
;         const f32x16 x0 = __builtin_amdgcn_mfma_f32_32x32x16_bf16(ucur, bb[0], z16, 0, 0, 0);
;         const f32x16 x1 = __builtin_amdgcn_mfma_f32_32x32x16_bf16(ucur, bb[1], z16, 0, 0, 0);
;         const f32x16 x2 = __builtin_amdgcn_mfma_f32_32x32x16_bf16(ucur, bb[2], z16, 0, 0, 0);
;         const f32x16 x3 = __builtin_amdgcn_mfma_f32_32x32x16_bf16(ucur, bb[3], z16, 0, 0, 0);
; #pragma unroll
;         for (int r = 0; r < 16; ++r) { const int t = crow(r, hi); XS[t * XS_STRIDE + ql] = pk2(x0[r], x2[r]); XS[t * XS_STRIDE + 32 + ql] = pk2(x1[r], x3[r]); }
;         LDS_FENCE();
; #pragma unroll
;         for (int tt = 0; tt < 32; ++tt) {
;             const int t = BWD ? 31 - tt : tt;
;             const unsigned v = XS[t * XS_STRIDE + lane];
;             const float nr = fmaf(ar, sr, fmaf(-ai, si, bflo(v))), ni = fmaf(ar, si, fmaf(ai, sr, bfhi(v)));
;             sr = nr; si = ni;
;             if (MODE > 0) XS[t * XS_STRIDE + lane] = pk2(sr, si);
	v_fmac_f32_e32 v198, v196, v195
	v_mul_f32_e32 v199, v197, v195
	v_fma_f32 v199, -v198, v196, v199
	v_mul_f32_e32 v200, v197, v196
	v_fmac_f32_e32 v200, v198, v195
	v_mul_f32_e32 v161, v197, v197
	v_fma_f32 v161, -v198, v198, v161
	v_mul_f32_e32 v214, v197, v198
	v_fmac_f32_e32 v214, v198, v197
	v_mov_b32_e32 v201, 1.0
	v_mov_b32_e32 v202, 0
	v_cndmask_b32_e32 v201, v201, v217, vcc
	v_cndmask_b32_e32 v202, v202, v194, vcc
	v_mul_f32_e32 v203, v201, v130
	v_fma_f32 v203, -v202, v131, v203
	v_mul_f32_e32 v204, v201, v131
	v_fmac_f32_e32 v204, v202, v130
	v_mul_f32_e32 v205, v201, v215
	v_fma_f32 v205, -v202, v216, v205
	v_mul_f32_e32 v206, v201, v216
	v_fmac_f32_e32 v206, v202, v215
	v_mul_f32_e32 v207, v205, v130
	v_fma_f32 v207, -v206, v131, v207
	v_mul_f32_e32 v208, v205, v131
	v_fmac_f32_e32 v208, v206, v130
	v_mov_b32_e32 v134, v201
	v_mov_b32_e32 v242, v202
	v_mov_b32_e32 v135, v203
	v_mov_b32_e32 v243, v204
	v_mov_b32_e32 v136, v205
	v_mov_b32_e32 v244, v206
	v_mov_b32_e32 v137, v207
	v_mov_b32_e32 v245, v208
	v_mul_f32_e32 v138, v201, v195
	v_fma_f32 v138, -v202, v196, v138
	v_mul_f32_e32 v246, v201, v196
	v_fmac_f32_e32 v246, v202, v195
	v_mul_f32_e32 v139, v203, v195
	v_fma_f32 v139, -v204, v196, v139
	v_mul_f32_e32 v247, v203, v196
	v_fmac_f32_e32 v247, v204, v195
	v_mul_f32_e32 v140, v205, v195
	v_fma_f32 v140, -v206, v196, v140
	v_mul_f32_e32 v248, v205, v196
	v_fmac_f32_e32 v248, v206, v195
	v_mul_f32_e32 v141, v207, v195
	v_fma_f32 v141, -v208, v196, v141
	v_mul_f32_e32 v249, v207, v196
	v_fmac_f32_e32 v249, v208, v195
	v_mul_f32_e32 v142, v201, v197
	v_fma_f32 v142, -v202, v198, v142
	v_mul_f32_e32 v250, v201, v198
	v_fmac_f32_e32 v250, v202, v197
	v_mul_f32_e32 v143, v203, v197
	v_fma_f32 v143, -v204, v198, v143
	v_mul_f32_e32 v251, v203, v198
	v_fmac_f32_e32 v251, v204, v197
	v_mul_f32_e32 v144, v205, v197
	v_fma_f32 v144, -v206, v198, v144
	v_mul_f32_e32 v252, v205, v198
	v_fmac_f32_e32 v252, v206, v197
	v_mul_f32_e32 v145, v207, v197
	v_fma_f32 v145, -v208, v198, v145
	v_mul_f32_e32 v253, v207, v198
	v_fmac_f32_e32 v253, v208, v197
	v_mul_f32_e32 v146, v201, v199
	v_fma_f32 v146, -v202, v200, v146
	v_mul_f32_e32 v210, v201, v200
	v_fmac_f32_e32 v210, v202, v199
	v_mul_f32_e32 v147, v203, v199
	v_fma_f32 v147, -v204, v200, v147
	v_mul_f32_e32 v211, v203, v200
	v_fmac_f32_e32 v211, v204, v199
	v_mul_f32_e32 v148, v205, v199
	v_fma_f32 v148, -v206, v200, v148
	v_mul_f32_e32 v212, v205, v200
	v_fmac_f32_e32 v212, v206, v199
	v_mul_f32_e32 v149, v207, v199
	v_fma_f32 v149, -v208, v200, v149
	v_mul_f32_e32 v213, v207, v200
	v_fmac_f32_e32 v213, v208, v199
	v_mov_b32_e32 v150, 0
	v_mov_b32_e32 v151, 0
	v_mov_b32_e32 v152, 0
	v_mov_b32_e32 v153, 0
	s_mov_b32 s22, 4
.Lp1b_loop:
	global_load_dwordx4 v[126:129], v[108:109], off
	v_lshl_add_u64 v[108:109], v[108:109], 0, s[68:69]
	s_waitcnt vmcnt(3)
	v_mfma_f32_32x32x16_bf16 v[2:17], v[114:117], v[74:77], 0
	v_mfma_f32_32x32x16_bf16 v[34:49], v[114:117], v[70:73], 0
	v_mfma_f32_32x32x16_bf16 v[18:33], v[114:117], v[66:69], 0
	v_mfma_f32_32x32x16_bf16 v[50:65], v[114:117], v[78:81], 0
	v_mul_f32_e32 v215, v160, v151
	v_mul_f32_e32 v216, v160, v150
	v_fma_f32 v150, v159, v150, -v215
	v_fma_f32 v151, v159, v151, v216
	v_mul_f32_e32 v215, v214, v153
	v_mul_f32_e32 v216, v214, v152
	v_fma_f32 v152, v161, v152, -v215
	v_fma_f32 v153, v161, v153, v216
	s_nop 3
	v_fmac_f32_e32 v150, v178, v2
	v_fmac_f32_e32 v151, v178, v34
	v_fma_f32 v150, -v226, v34, v150
	v_fmac_f32_e32 v151, v226, v2
	v_mul_f32_e32 v217, v179, v3
	v_mul_f32_e32 v194, v179, v35
	v_fma_f32 v217, -v227, v35, v217
	v_fmac_f32_e32 v194, v227, v3
	v_fmac_f32_e32 v150, v180, v4
	v_fmac_f32_e32 v151, v180, v36
	v_fma_f32 v150, -v228, v36, v150
	v_fmac_f32_e32 v151, v228, v4
	v_fmac_f32_e32 v217, v181, v5
	v_fmac_f32_e32 v194, v181, v37
	v_fma_f32 v217, -v229, v37, v217
	v_fmac_f32_e32 v194, v229, v5
	v_fmac_f32_e32 v150, v182, v6
	v_fmac_f32_e32 v151, v182, v38
	v_fma_f32 v150, -v230, v38, v150
	v_fmac_f32_e32 v151, v230, v6
	v_fmac_f32_e32 v217, v183, v7
	v_fmac_f32_e32 v194, v183, v39
	v_fma_f32 v217, -v231, v39, v217
	v_fmac_f32_e32 v194, v231, v7
	v_fmac_f32_e32 v150, v184, v8
	v_fmac_f32_e32 v151, v184, v40
	v_fma_f32 v150, -v232, v40, v150
	v_fmac_f32_e32 v151, v232, v8
	v_fmac_f32_e32 v217, v185, v9
	v_fmac_f32_e32 v194, v185, v41
	v_fma_f32 v217, -v233, v41, v217
	v_fmac_f32_e32 v194, v233, v9
	v_fmac_f32_e32 v150, v186, v10
	v_fmac_f32_e32 v151, v186, v42
	v_fma_f32 v150, -v234, v42, v150
	v_fmac_f32_e32 v151, v234, v10
	v_fmac_f32_e32 v217, v187, v11
	v_fmac_f32_e32 v194, v187, v43
	v_fma_f32 v217, -v235, v43, v217
	v_fmac_f32_e32 v194, v235, v11
	v_fmac_f32_e32 v150, v188, v12
	v_fmac_f32_e32 v151, v188, v44
	v_fma_f32 v150, -v236, v44, v150
	v_fmac_f32_e32 v151, v236, v12
	v_fmac_f32_e32 v217, v189, v13
	v_fmac_f32_e32 v194, v189, v45
	v_fma_f32 v217, -v237, v45, v217
	v_fmac_f32_e32 v194, v237, v13
	v_fmac_f32_e32 v150, v190, v14
	v_fmac_f32_e32 v151, v190, v46
	v_fma_f32 v150, -v238, v46, v150
	v_fmac_f32_e32 v151, v238, v14
	v_fmac_f32_e32 v217, v191, v15
	v_fmac_f32_e32 v194, v191, v47
	v_fma_f32 v217, -v239, v47, v217
	v_fmac_f32_e32 v194, v239, v15
	v_fmac_f32_e32 v150, v192, v16
	v_fmac_f32_e32 v151, v192, v48
	v_fma_f32 v150, -v240, v48, v150
	v_fmac_f32_e32 v151, v240, v16
	v_fmac_f32_e32 v217, v193, v17
	v_fmac_f32_e32 v194, v193, v49
	v_fma_f32 v217, -v241, v49, v217
	v_fmac_f32_e32 v194, v241, v17
	v_add_f32_e32 v150, v150, v217
	v_add_f32_e32 v151, v151, v194
	v_fmac_f32_e32 v152, v134, v18
	v_fmac_f32_e32 v153, v134, v50
	v_fma_f32 v152, -v242, v50, v152
	v_fmac_f32_e32 v153, v242, v18
; __device__ __forceinline__ unsigned pk2(float lo, float hi) { const f32x2 v = {lo, hi}; return __builtin_bit_cast(unsigned, __builtin_convertvector(v, bf16x2_t)); }
; __device__ __forceinline__ float bflo(unsigned w) { return __uint_as_float(w << 16); }
; __device__ __forceinline__ float bfhi(unsigned w) { return __uint_as_float(w & 0xffff0000u); }
; #define LDS_FENCE() asm volatile("s_waitcnt lgkmcnt(0)" ::: "memory")
; template <bool BWD, int MODE  >
; __device__ __forceinline__ void ssm_pass(const bf16* proj, int rowbase, int g, const bf16x8* BBp, const bf16x8* CCp, float ar, float ai, float& sr, float& si,
;                                          LAS unsigned* XS, int lane, f32x4* ysc, const float* Dp, bf16* zbuf) {
;     ...
;     for (int c = 0; c < 16; ++c) {
;         const int ch = BWD ? 15 - c : c;
;         bf16x8 unext = ucur;
;         if (c < 15) unext = *(const bf16x8*)(up + (size_t)(BWD ? ch - 1 : ch + 1) * 32 * DIN);
;         f32x4 y0 = (f32x4){0.f, 0.f, 0.f, 0.f}, y1 = y0; bf16 uvl[8];
;         if (MODE == 2) {
;             y0 = ysc[(ch * 2 + 0) * 64 + lane]; y1 = ysc[(ch * 2 + 1) * 64 + lane];
; #pragma unroll
;             for (int q = 0; q < 8; ++q) uvl[q] = proj[(size_t)(rowbase + 32 * ch + 16 * (q >> 2) + 4 * (lane >> 4) + (q & 3)) * DIN + 768 + g * 16 + (lane & 15)];
;         }
;         f32x16 z16;
; #pragma unroll
;         for (int r = 0; r < 16; ++r) z16[r] = 0.f;
;         const f32x16 x0 = __builtin_amdgcn_mfma_f32_32x32x16_bf16(ucur, bb[0], z16, 0, 0, 0);
;         const f32x16 x1 = __builtin_amdgcn_mfma_f32_32x32x16_bf16(ucur, bb[1], z16, 0, 0, 0);
;         const f32x16 x2 = __builtin_amdgcn_mfma_f32_32x32x16_bf16(ucur, bb[2], z16, 0, 0, 0);
;         const f32x16 x3 = __builtin_amdgcn_mfma_f32_32x32x16_bf16(ucur, bb[3], z16, 0, 0, 0);
; #pragma unroll
;         for (int r = 0; r < 16; ++r) { const int t = crow(r, hi); XS[t * XS_STRIDE + ql] = pk2(x0[r], x2[r]); XS[t * XS_STRIDE + 32 + ql] = pk2(x1[r], x3[r]); }
;         LDS_FENCE();
; #pragma unroll
;         for (int tt = 0; tt < 32; ++tt) {
;             const int t = BWD ? 31 - tt : tt;
;             const unsigned v = XS[t * XS_STRIDE + lane];
;             const float nr = fmaf(ar, sr, fmaf(-ai, si, bflo(v))), ni = fmaf(ar, si, fmaf(ai, sr, bfhi(v)));
;             sr = nr; si = ni;
;             if (MODE > 0) XS[t * XS_STRIDE + lane] = pk2(sr, si);
	v_mul_f32_e32 v195, v135, v19
	v_mul_f32_e32 v196, v135, v51
	v_fma_f32 v195, -v243, v51, v195
	v_fmac_f32_e32 v196, v243, v19
	v_fmac_f32_e32 v152, v136, v20
	v_fmac_f32_e32 v153, v136, v52
	v_fma_f32 v152, -v244, v52, v152
	v_fmac_f32_e32 v153, v244, v20
	v_fmac_f32_e32 v195, v137, v21
	v_fmac_f32_e32 v196, v137, v53
	v_fma_f32 v195, -v245, v53, v195
	v_fmac_f32_e32 v196, v245, v21
	v_fmac_f32_e32 v152, v138, v22
	v_fmac_f32_e32 v153, v138, v54
	v_fma_f32 v152, -v246, v54, v152
	v_fmac_f32_e32 v153, v246, v22
	v_fmac_f32_e32 v195, v139, v23
	v_fmac_f32_e32 v196, v139, v55
	v_fma_f32 v195, -v247, v55, v195
	v_fmac_f32_e32 v196, v247, v23
	v_fmac_f32_e32 v152, v140, v24
	v_fmac_f32_e32 v153, v140, v56
	v_fma_f32 v152, -v248, v56, v152
	v_fmac_f32_e32 v153, v248, v24
	v_fmac_f32_e32 v195, v141, v25
	v_fmac_f32_e32 v196, v141, v57
	v_fma_f32 v195, -v249, v57, v195
	v_fmac_f32_e32 v196, v249, v25
	v_fmac_f32_e32 v152, v142, v26
	v_fmac_f32_e32 v153, v142, v58
	v_fma_f32 v152, -v250, v58, v152
	v_fmac_f32_e32 v153, v250, v26
	v_fmac_f32_e32 v195, v143, v27
	v_fmac_f32_e32 v196, v143, v59
	v_fma_f32 v195, -v251, v59, v195
	v_fmac_f32_e32 v196, v251, v27
	v_fmac_f32_e32 v152, v144, v28
	v_fmac_f32_e32 v153, v144, v60
	v_fma_f32 v152, -v252, v60, v152
	v_fmac_f32_e32 v153, v252, v28
	v_fmac_f32_e32 v195, v145, v29
	v_fmac_f32_e32 v196, v145, v61
	v_fma_f32 v195, -v253, v61, v195
	v_fmac_f32_e32 v196, v253, v29
	v_fmac_f32_e32 v152, v146, v30
	v_fmac_f32_e32 v153, v146, v62
	v_fma_f32 v152, -v210, v62, v152
	v_fmac_f32_e32 v153, v210, v30
	v_fmac_f32_e32 v195, v147, v31
	v_fmac_f32_e32 v196, v147, v63
	v_fma_f32 v195, -v211, v63, v195
	v_fmac_f32_e32 v196, v211, v31
	v_fmac_f32_e32 v152, v148, v32
	v_fmac_f32_e32 v153, v148, v64
	v_fma_f32 v152, -v212, v64, v152
	v_fmac_f32_e32 v153, v212, v32
	v_fmac_f32_e32 v195, v149, v33
	v_fmac_f32_e32 v196, v149, v65
	v_fma_f32 v195, -v213, v65, v195
	v_fmac_f32_e32 v196, v213, v33
	v_add_f32_e32 v152, v152, v195
	v_add_f32_e32 v153, v153, v196
	global_load_dwordx4 v[114:117], v[108:109], off
	v_lshl_add_u64 v[108:109], v[108:109], 0, s[68:69]
	s_waitcnt vmcnt(3)
	v_mfma_f32_32x32x16_bf16 v[2:17], v[118:121], v[74:77], 0
	v_mfma_f32_32x32x16_bf16 v[34:49], v[118:121], v[70:73], 0
	v_mfma_f32_32x32x16_bf16 v[18:33], v[118:121], v[66:69], 0
	v_mfma_f32_32x32x16_bf16 v[50:65], v[118:121], v[78:81], 0
	v_mul_f32_e32 v215, v160, v151
	v_mul_f32_e32 v216, v160, v150
	v_fma_f32 v150, v159, v150, -v215
	v_fma_f32 v151, v159, v151, v216
	v_mul_f32_e32 v215, v214, v153
	v_mul_f32_e32 v216, v214, v152
	v_fma_f32 v152, v161, v152, -v215
	v_fma_f32 v153, v161, v153, v216
	s_nop 3
	v_fmac_f32_e32 v150, v178, v2
	v_fmac_f32_e32 v151, v178, v34
	v_fma_f32 v150, -v226, v34, v150
	v_fmac_f32_e32 v151, v226, v2
	v_mul_f32_e32 v217, v179, v3
	v_mul_f32_e32 v194, v179, v35
	v_fma_f32 v217, -v227, v35, v217
	v_fmac_f32_e32 v194, v227, v3
	v_fmac_f32_e32 v150, v180, v4
	v_fmac_f32_e32 v151, v180, v36
	v_fma_f32 v150, -v228, v36, v150
	v_fmac_f32_e32 v151, v228, v4
	v_fmac_f32_e32 v217, v181, v5
	v_fmac_f32_e32 v194, v181, v37
	v_fma_f32 v217, -v229, v37, v217
	v_fmac_f32_e32 v194, v229, v5
	v_fmac_f32_e32 v150, v182, v6
	v_fmac_f32_e32 v151, v182, v38
	v_fma_f32 v150, -v230, v38, v150
	v_fmac_f32_e32 v151, v230, v6
	v_fmac_f32_e32 v217, v183, v7
	v_fmac_f32_e32 v194, v183, v39
	v_fma_f32 v217, -v231, v39, v217
	v_fmac_f32_e32 v194, v231, v7
	v_fmac_f32_e32 v150, v184, v8
	v_fmac_f32_e32 v151, v184, v40
	v_fma_f32 v150, -v232, v40, v150
	v_fmac_f32_e32 v151, v232, v8
	v_fmac_f32_e32 v217, v185, v9
	v_fmac_f32_e32 v194, v185, v41
	v_fma_f32 v217, -v233, v41, v217
	v_fmac_f32_e32 v194, v233, v9
	v_fmac_f32_e32 v150, v186, v10
	v_fmac_f32_e32 v151, v186, v42
	v_fma_f32 v150, -v234, v42, v150
	v_fmac_f32_e32 v151, v234, v10
	v_fmac_f32_e32 v217, v187, v11
	v_fmac_f32_e32 v194, v187, v43
	v_fma_f32 v217, -v235, v43, v217
	v_fmac_f32_e32 v194, v235, v11
	v_fmac_f32_e32 v150, v188, v12
	v_fmac_f32_e32 v151, v188, v44
	v_fma_f32 v150, -v236, v44, v150
	v_fmac_f32_e32 v151, v236, v12
	v_fmac_f32_e32 v217, v189, v13
	v_fmac_f32_e32 v194, v189, v45
	v_fma_f32 v217, -v237, v45, v217
	v_fmac_f32_e32 v194, v237, v13
	v_fmac_f32_e32 v150, v190, v14
	v_fmac_f32_e32 v151, v190, v46
	v_fma_f32 v150, -v238, v46, v150
	v_fmac_f32_e32 v151, v238, v14
	v_fmac_f32_e32 v217, v191, v15
	v_fmac_f32_e32 v194, v191, v47
	v_fma_f32 v217, -v239, v47, v217
	v_fmac_f32_e32 v194, v239, v15
	v_fmac_f32_e32 v150, v192, v16
	v_fmac_f32_e32 v151, v192, v48
	v_fma_f32 v150, -v240, v48, v150
	v_fmac_f32_e32 v151, v240, v16
	v_fmac_f32_e32 v217, v193, v17
	v_fmac_f32_e32 v194, v193, v49
	v_fma_f32 v217, -v241, v49, v217
	v_fmac_f32_e32 v194, v241, v17
	v_add_f32_e32 v150, v150, v217
	v_add_f32_e32 v151, v151, v194
	v_fmac_f32_e32 v152, v134, v18
	v_fmac_f32_e32 v153, v134, v50
	v_fma_f32 v152, -v242, v50, v152
	v_fmac_f32_e32 v153, v242, v18
	v_mul_f32_e32 v195, v135, v19
	v_mul_f32_e32 v196, v135, v51
	v_fma_f32 v195, -v243, v51, v195
	v_fmac_f32_e32 v196, v243, v19
	v_fmac_f32_e32 v152, v136, v20
	v_fmac_f32_e32 v153, v136, v52
	v_fma_f32 v152, -v244, v52, v152
	v_fmac_f32_e32 v153, v244, v20
	v_fmac_f32_e32 v195, v137, v21
	v_fmac_f32_e32 v196, v137, v53
	v_fma_f32 v195, -v245, v53, v195
	v_fmac_f32_e32 v196, v245, v21
	v_fmac_f32_e32 v152, v138, v22
	v_fmac_f32_e32 v153, v138, v54
	v_fma_f32 v152, -v246, v54, v152
	v_fmac_f32_e32 v153, v246, v22
	v_fmac_f32_e32 v195, v139, v23
	v_fmac_f32_e32 v196, v139, v55
	v_fma_f32 v195, -v247, v55, v195
	v_fmac_f32_e32 v196, v247, v23
	v_fmac_f32_e32 v152, v140, v24
	v_fmac_f32_e32 v153, v140, v56
	v_fma_f32 v152, -v248, v56, v152
	v_fmac_f32_e32 v153, v248, v24
	v_fmac_f32_e32 v195, v141, v25
	v_fmac_f32_e32 v196, v141, v57
	v_fma_f32 v195, -v249, v57, v195
	v_fmac_f32_e32 v196, v249, v25
	v_fmac_f32_e32 v152, v142, v26
	v_fmac_f32_e32 v153, v142, v58
	v_fma_f32 v152, -v250, v58, v152
	v_fmac_f32_e32 v153, v250, v26
	v_fmac_f32_e32 v195, v143, v27
	v_fmac_f32_e32 v196, v143, v59
	v_fma_f32 v195, -v251, v59, v195
	v_fmac_f32_e32 v196, v251, v27
	v_fmac_f32_e32 v152, v144, v28
	v_fmac_f32_e32 v153, v144, v60
	v_fma_f32 v152, -v252, v60, v152
	v_fmac_f32_e32 v153, v252, v28
	v_fmac_f32_e32 v195, v145, v29
	v_fmac_f32_e32 v196, v145, v61
	v_fma_f32 v195, -v253, v61, v195
	v_fmac_f32_e32 v196, v253, v29
	v_fmac_f32_e32 v152, v146, v30
	v_fmac_f32_e32 v153, v146, v62
	v_fma_f32 v152, -v210, v62, v152
	v_fmac_f32_e32 v153, v210, v30
	v_fmac_f32_e32 v195, v147, v31
	v_fmac_f32_e32 v196, v147, v63
	v_fma_f32 v195, -v211, v63, v195
	v_fmac_f32_e32 v196, v211, v31
	v_fmac_f32_e32 v152, v148, v32
	v_fmac_f32_e32 v153, v148, v64
	v_fma_f32 v152, -v212, v64, v152
	v_fmac_f32_e32 v153, v212, v32
	v_fmac_f32_e32 v195, v149, v33
	v_fmac_f32_e32 v196, v149, v65
	v_fma_f32 v195, -v213, v65, v195
	v_fmac_f32_e32 v196, v213, v33
	v_add_f32_e32 v152, v152, v195
	v_add_f32_e32 v153, v153, v196
	global_load_dwordx4 v[118:121], v[108:109], off
	v_lshl_add_u64 v[108:109], v[108:109], 0, s[68:69]
	s_waitcnt vmcnt(3)
; __device__ __forceinline__ unsigned pk2(float lo, float hi) { const f32x2 v = {lo, hi}; return __builtin_bit_cast(unsigned, __builtin_convertvector(v, bf16x2_t)); }
; __device__ __forceinline__ float bflo(unsigned w) { return __uint_as_float(w << 16); }
; __device__ __forceinline__ float bfhi(unsigned w) { return __uint_as_float(w & 0xffff0000u); }
; #define LDS_FENCE() asm volatile("s_waitcnt lgkmcnt(0)" ::: "memory")
; template <bool BWD, int MODE  >
; __device__ __forceinline__ void ssm_pass(const bf16* proj, int rowbase, int g, const bf16x8* BBp, const bf16x8* CCp, float ar, float ai, float& sr, float& si,
;                                          LAS unsigned* XS, int lane, f32x4* ysc, const float* Dp, bf16* zbuf) {
;     ...
;     for (int c = 0; c < 16; ++c) {
;         const int ch = BWD ? 15 - c : c;
;         bf16x8 unext = ucur;
;         if (c < 15) unext = *(const bf16x8*)(up + (size_t)(BWD ? ch - 1 : ch + 1) * 32 * DIN);
;         f32x4 y0 = (f32x4){0.f, 0.f, 0.f, 0.f}, y1 = y0; bf16 uvl[8];
;         if (MODE == 2) {
;             y0 = ysc[(ch * 2 + 0) * 64 + lane]; y1 = ysc[(ch * 2 + 1) * 64 + lane];
; #pragma unroll
;             for (int q = 0; q < 8; ++q) uvl[q] = proj[(size_t)(rowbase + 32 * ch + 16 * (q >> 2) + 4 * (lane >> 4) + (q & 3)) * DIN + 768 + g * 16 + (lane & 15)];
;         }
;         f32x16 z16;
; #pragma unroll
;         for (int r = 0; r < 16; ++r) z16[r] = 0.f;
;         const f32x16 x0 = __builtin_amdgcn_mfma_f32_32x32x16_bf16(ucur, bb[0], z16, 0, 0, 0);
;         const f32x16 x1 = __builtin_amdgcn_mfma_f32_32x32x16_bf16(ucur, bb[1], z16, 0, 0, 0);
;         const f32x16 x2 = __builtin_amdgcn_mfma_f32_32x32x16_bf16(ucur, bb[2], z16, 0, 0, 0);
;         const f32x16 x3 = __builtin_amdgcn_mfma_f32_32x32x16_bf16(ucur, bb[3], z16, 0, 0, 0);
; #pragma unroll
;         for (int r = 0; r < 16; ++r) { const int t = crow(r, hi); XS[t * XS_STRIDE + ql] = pk2(x0[r], x2[r]); XS[t * XS_STRIDE + 32 + ql] = pk2(x1[r], x3[r]); }
;         LDS_FENCE();
; #pragma unroll
;         for (int tt = 0; tt < 32; ++tt) {
;             const int t = BWD ? 31 - tt : tt;
;             const unsigned v = XS[t * XS_STRIDE + lane];
;             const float nr = fmaf(ar, sr, fmaf(-ai, si, bflo(v))), ni = fmaf(ar, si, fmaf(ai, sr, bfhi(v)));
;             sr = nr; si = ni;
;             if (MODE > 0) XS[t * XS_STRIDE + lane] = pk2(sr, si);
	v_mfma_f32_32x32x16_bf16 v[2:17], v[122:125], v[74:77], 0
	v_mfma_f32_32x32x16_bf16 v[34:49], v[122:125], v[70:73], 0
	v_mfma_f32_32x32x16_bf16 v[18:33], v[122:125], v[66:69], 0
	v_mfma_f32_32x32x16_bf16 v[50:65], v[122:125], v[78:81], 0
	v_mul_f32_e32 v215, v160, v151
	v_mul_f32_e32 v216, v160, v150
	v_fma_f32 v150, v159, v150, -v215
	v_fma_f32 v151, v159, v151, v216
	v_mul_f32_e32 v215, v214, v153
	v_mul_f32_e32 v216, v214, v152
	v_fma_f32 v152, v161, v152, -v215
	v_fma_f32 v153, v161, v153, v216
	s_nop 3
	v_fmac_f32_e32 v150, v178, v2
	v_fmac_f32_e32 v151, v178, v34
	v_fma_f32 v150, -v226, v34, v150
	v_fmac_f32_e32 v151, v226, v2
	v_mul_f32_e32 v217, v179, v3
	v_mul_f32_e32 v194, v179, v35
	v_fma_f32 v217, -v227, v35, v217
	v_fmac_f32_e32 v194, v227, v3
	v_fmac_f32_e32 v150, v180, v4
	v_fmac_f32_e32 v151, v180, v36
	v_fma_f32 v150, -v228, v36, v150
	v_fmac_f32_e32 v151, v228, v4
	v_fmac_f32_e32 v217, v181, v5
	v_fmac_f32_e32 v194, v181, v37
	v_fma_f32 v217, -v229, v37, v217
	v_fmac_f32_e32 v194, v229, v5
	v_fmac_f32_e32 v150, v182, v6
	v_fmac_f32_e32 v151, v182, v38
	v_fma_f32 v150, -v230, v38, v150
	v_fmac_f32_e32 v151, v230, v6
	v_fmac_f32_e32 v217, v183, v7
	v_fmac_f32_e32 v194, v183, v39
	v_fma_f32 v217, -v231, v39, v217
	v_fmac_f32_e32 v194, v231, v7
	v_fmac_f32_e32 v150, v184, v8
	v_fmac_f32_e32 v151, v184, v40
	v_fma_f32 v150, -v232, v40, v150
	v_fmac_f32_e32 v151, v232, v8
	v_fmac_f32_e32 v217, v185, v9
	v_fmac_f32_e32 v194, v185, v41
	v_fma_f32 v217, -v233, v41, v217
	v_fmac_f32_e32 v194, v233, v9
	v_fmac_f32_e32 v150, v186, v10
	v_fmac_f32_e32 v151, v186, v42
	v_fma_f32 v150, -v234, v42, v150
	v_fmac_f32_e32 v151, v234, v10
	v_fmac_f32_e32 v217, v187, v11
	v_fmac_f32_e32 v194, v187, v43
	v_fma_f32 v217, -v235, v43, v217
	v_fmac_f32_e32 v194, v235, v11
	v_fmac_f32_e32 v150, v188, v12
	v_fmac_f32_e32 v151, v188, v44
	v_fma_f32 v150, -v236, v44, v150
	v_fmac_f32_e32 v151, v236, v12
	v_fmac_f32_e32 v217, v189, v13
	v_fmac_f32_e32 v194, v189, v45
	v_fma_f32 v217, -v237, v45, v217
	v_fmac_f32_e32 v194, v237, v13
	v_fmac_f32_e32 v150, v190, v14
	v_fmac_f32_e32 v151, v190, v46
	v_fma_f32 v150, -v238, v46, v150
	v_fmac_f32_e32 v151, v238, v14
	v_fmac_f32_e32 v217, v191, v15
	v_fmac_f32_e32 v194, v191, v47
	v_fma_f32 v217, -v239, v47, v217
	v_fmac_f32_e32 v194, v239, v15
	v_fmac_f32_e32 v150, v192, v16
	v_fmac_f32_e32 v151, v192, v48
	v_fma_f32 v150, -v240, v48, v150
	v_fmac_f32_e32 v151, v240, v16
	v_fmac_f32_e32 v217, v193, v17
	v_fmac_f32_e32 v194, v193, v49
	v_fma_f32 v217, -v241, v49, v217
	v_fmac_f32_e32 v194, v241, v17
	v_add_f32_e32 v150, v150, v217
	v_add_f32_e32 v151, v151, v194
	v_fmac_f32_e32 v152, v134, v18
	v_fmac_f32_e32 v153, v134, v50
	v_fma_f32 v152, -v242, v50, v152
	v_fmac_f32_e32 v153, v242, v18
	v_mul_f32_e32 v195, v135, v19
	v_mul_f32_e32 v196, v135, v51
	v_fma_f32 v195, -v243, v51, v195
	v_fmac_f32_e32 v196, v243, v19
	v_fmac_f32_e32 v152, v136, v20
	v_fmac_f32_e32 v153, v136, v52
	v_fma_f32 v152, -v244, v52, v152
	v_fmac_f32_e32 v153, v244, v20
	v_fmac_f32_e32 v195, v137, v21
	v_fmac_f32_e32 v196, v137, v53
	v_fma_f32 v195, -v245, v53, v195
	v_fmac_f32_e32 v196, v245, v21
	v_fmac_f32_e32 v152, v138, v22
	v_fmac_f32_e32 v153, v138, v54
	v_fma_f32 v152, -v246, v54, v152
	v_fmac_f32_e32 v153, v246, v22
	v_fmac_f32_e32 v195, v139, v23
	v_fmac_f32_e32 v196, v139, v55
	v_fma_f32 v195, -v247, v55, v195
	v_fmac_f32_e32 v196, v247, v23
	v_fmac_f32_e32 v152, v140, v24
	v_fmac_f32_e32 v153, v140, v56
	v_fma_f32 v152, -v248, v56, v152
	v_fmac_f32_e32 v153, v248, v24
	v_fmac_f32_e32 v195, v141, v25
	v_fmac_f32_e32 v196, v141, v57
	v_fma_f32 v195, -v249, v57, v195
	v_fmac_f32_e32 v196, v249, v25
	v_fmac_f32_e32 v152, v142, v26
	v_fmac_f32_e32 v153, v142, v58
	v_fma_f32 v152, -v250, v58, v152
	v_fmac_f32_e32 v153, v250, v26
	v_fmac_f32_e32 v195, v143, v27
	v_fmac_f32_e32 v196, v143, v59
	v_fma_f32 v195, -v251, v59, v195
	v_fmac_f32_e32 v196, v251, v27
	v_fmac_f32_e32 v152, v144, v28
	v_fmac_f32_e32 v153, v144, v60
	v_fma_f32 v152, -v252, v60, v152
	v_fmac_f32_e32 v153, v252, v28
	v_fmac_f32_e32 v195, v145, v29
	v_fmac_f32_e32 v196, v145, v61
	v_fma_f32 v195, -v253, v61, v195
	v_fmac_f32_e32 v196, v253, v29
	v_fmac_f32_e32 v152, v146, v30
	v_fmac_f32_e32 v153, v146, v62
	v_fma_f32 v152, -v210, v62, v152
	v_fmac_f32_e32 v153, v210, v30
	v_fmac_f32_e32 v195, v147, v31
	v_fmac_f32_e32 v196, v147, v63
	v_fma_f32 v195, -v211, v63, v195
	v_fmac_f32_e32 v196, v211, v31
	v_fmac_f32_e32 v152, v148, v32
	v_fmac_f32_e32 v153, v148, v64
	v_fma_f32 v152, -v212, v64, v152
	v_fmac_f32_e32 v153, v212, v32
	v_fmac_f32_e32 v195, v149, v33
	v_fmac_f32_e32 v196, v149, v65
	v_fma_f32 v195, -v213, v65, v195
	v_fmac_f32_e32 v196, v213, v33
	v_add_f32_e32 v152, v152, v195
	v_add_f32_e32 v153, v153, v196
	global_load_dwordx4 v[122:125], v[108:109], off
	v_lshl_add_u64 v[108:109], v[108:109], 0, s[68:69]
	s_waitcnt vmcnt(3)
; __device__ __forceinline__ unsigned pk2(float lo, float hi) { const f32x2 v = {lo, hi}; return __builtin_bit_cast(unsigned, __builtin_convertvector(v, bf16x2_t)); }
; __device__ __forceinline__ float bflo(unsigned w) { return __uint_as_float(w << 16); }
; __device__ __forceinline__ float bfhi(unsigned w) { return __uint_as_float(w & 0xffff0000u); }
; #define LDS_FENCE() asm volatile("s_waitcnt lgkmcnt(0)" ::: "memory")
; template <bool BWD, int MODE  >
; __device__ __forceinline__ void ssm_pass(const bf16* proj, int rowbase, int g, const bf16x8* BBp, const bf16x8* CCp, float ar, float ai, float& sr, float& si,
;                                          LAS unsigned* XS, int lane, f32x4* ysc, const float* Dp, bf16* zbuf) {
;     ...
;     for (int c = 0; c < 16; ++c) {
;         const int ch = BWD ? 15 - c : c;
;         bf16x8 unext = ucur;
;         if (c < 15) unext = *(const bf16x8*)(up + (size_t)(BWD ? ch - 1 : ch + 1) * 32 * DIN);
;         f32x4 y0 = (f32x4){0.f, 0.f, 0.f, 0.f}, y1 = y0; bf16 uvl[8];
;         if (MODE == 2) {
;             y0 = ysc[(ch * 2 + 0) * 64 + lane]; y1 = ysc[(ch * 2 + 1) * 64 + lane];
; #pragma unroll
;             for (int q = 0; q < 8; ++q) uvl[q] = proj[(size_t)(rowbase + 32 * ch + 16 * (q >> 2) + 4 * (lane >> 4) + (q & 3)) * DIN + 768 + g * 16 + (lane & 15)];
;         }
;         f32x16 z16;
; #pragma unroll
;         for (int r = 0; r < 16; ++r) z16[r] = 0.f;
;         const f32x16 x0 = __builtin_amdgcn_mfma_f32_32x32x16_bf16(ucur, bb[0], z16, 0, 0, 0);
;         const f32x16 x1 = __builtin_amdgcn_mfma_f32_32x32x16_bf16(ucur, bb[1], z16, 0, 0, 0);
;         const f32x16 x2 = __builtin_amdgcn_mfma_f32_32x32x16_bf16(ucur, bb[2], z16, 0, 0, 0);
;         const f32x16 x3 = __builtin_amdgcn_mfma_f32_32x32x16_bf16(ucur, bb[3], z16, 0, 0, 0);
; #pragma unroll
;         for (int r = 0; r < 16; ++r) { const int t = crow(r, hi); XS[t * XS_STRIDE + ql] = pk2(x0[r], x2[r]); XS[t * XS_STRIDE + 32 + ql] = pk2(x1[r], x3[r]); }
;         LDS_FENCE();
; #pragma unroll
;         for (int tt = 0; tt < 32; ++tt) {
;             const int t = BWD ? 31 - tt : tt;
;             const unsigned v = XS[t * XS_STRIDE + lane];
;             const float nr = fmaf(ar, sr, fmaf(-ai, si, bflo(v))), ni = fmaf(ar, si, fmaf(ai, sr, bfhi(v)));
;             sr = nr; si = ni;
;             if (MODE > 0) XS[t * XS_STRIDE + lane] = pk2(sr, si);
	v_mfma_f32_32x32x16_bf16 v[2:17], v[126:129], v[74:77], 0
	v_mfma_f32_32x32x16_bf16 v[34:49], v[126:129], v[70:73], 0
	v_mfma_f32_32x32x16_bf16 v[18:33], v[126:129], v[66:69], 0
	v_mfma_f32_32x32x16_bf16 v[50:65], v[126:129], v[78:81], 0
	v_mul_f32_e32 v215, v160, v151
	v_mul_f32_e32 v216, v160, v150
	v_fma_f32 v150, v159, v150, -v215
	v_fma_f32 v151, v159, v151, v216
	v_mul_f32_e32 v215, v214, v153
	v_mul_f32_e32 v216, v214, v152
	v_fma_f32 v152, v161, v152, -v215
	v_fma_f32 v153, v161, v153, v216
	s_nop 3
	v_fmac_f32_e32 v150, v178, v2
	v_fmac_f32_e32 v151, v178, v34
	v_fma_f32 v150, -v226, v34, v150
	v_fmac_f32_e32 v151, v226, v2
	v_mul_f32_e32 v217, v179, v3
	v_mul_f32_e32 v194, v179, v35
	v_fma_f32 v217, -v227, v35, v217
	v_fmac_f32_e32 v194, v227, v3
	v_fmac_f32_e32 v150, v180, v4
	v_fmac_f32_e32 v151, v180, v36
	v_fma_f32 v150, -v228, v36, v150
	v_fmac_f32_e32 v151, v228, v4
	v_fmac_f32_e32 v217, v181, v5
	v_fmac_f32_e32 v194, v181, v37
	v_fma_f32 v217, -v229, v37, v217
	v_fmac_f32_e32 v194, v229, v5
	v_fmac_f32_e32 v150, v182, v6
	v_fmac_f32_e32 v151, v182, v38
	v_fma_f32 v150, -v230, v38, v150
	v_fmac_f32_e32 v151, v230, v6
	v_fmac_f32_e32 v217, v183, v7
	v_fmac_f32_e32 v194, v183, v39
	v_fma_f32 v217, -v231, v39, v217
	v_fmac_f32_e32 v194, v231, v7
	v_fmac_f32_e32 v150, v184, v8
	v_fmac_f32_e32 v151, v184, v40
	v_fma_f32 v150, -v232, v40, v150
	v_fmac_f32_e32 v151, v232, v8
	v_fmac_f32_e32 v217, v185, v9
	v_fmac_f32_e32 v194, v185, v41
	v_fma_f32 v217, -v233, v41, v217
	v_fmac_f32_e32 v194, v233, v9
	v_fmac_f32_e32 v150, v186, v10
	v_fmac_f32_e32 v151, v186, v42
	v_fma_f32 v150, -v234, v42, v150
	v_fmac_f32_e32 v151, v234, v10
	v_fmac_f32_e32 v217, v187, v11
	v_fmac_f32_e32 v194, v187, v43
	v_fma_f32 v217, -v235, v43, v217
	v_fmac_f32_e32 v194, v235, v11
	v_fmac_f32_e32 v150, v188, v12
	v_fmac_f32_e32 v151, v188, v44
	v_fma_f32 v150, -v236, v44, v150
	v_fmac_f32_e32 v151, v236, v12
	v_fmac_f32_e32 v217, v189, v13
	v_fmac_f32_e32 v194, v189, v45
	v_fma_f32 v217, -v237, v45, v217
	v_fmac_f32_e32 v194, v237, v13
	v_fmac_f32_e32 v150, v190, v14
	v_fmac_f32_e32 v151, v190, v46
	v_fma_f32 v150, -v238, v46, v150
	v_fmac_f32_e32 v151, v238, v14
	v_fmac_f32_e32 v217, v191, v15
	v_fmac_f32_e32 v194, v191, v47
	v_fma_f32 v217, -v239, v47, v217
	v_fmac_f32_e32 v194, v239, v15
	v_fmac_f32_e32 v150, v192, v16
	v_fmac_f32_e32 v151, v192, v48
	v_fma_f32 v150, -v240, v48, v150
	v_fmac_f32_e32 v151, v240, v16
	v_fmac_f32_e32 v217, v193, v17
	v_fmac_f32_e32 v194, v193, v49
	v_fma_f32 v217, -v241, v49, v217
	v_fmac_f32_e32 v194, v241, v17
	v_add_f32_e32 v150, v150, v217
	v_add_f32_e32 v151, v151, v194
	v_fmac_f32_e32 v152, v134, v18
	v_fmac_f32_e32 v153, v134, v50
	v_fma_f32 v152, -v242, v50, v152
	v_fmac_f32_e32 v153, v242, v18
	v_mul_f32_e32 v195, v135, v19
	v_mul_f32_e32 v196, v135, v51
	v_fma_f32 v195, -v243, v51, v195
	v_fmac_f32_e32 v196, v243, v19
	v_fmac_f32_e32 v152, v136, v20
	v_fmac_f32_e32 v153, v136, v52
	v_fma_f32 v152, -v244, v52, v152
	v_fmac_f32_e32 v153, v244, v20
	v_fmac_f32_e32 v195, v137, v21
	v_fmac_f32_e32 v196, v137, v53
	v_fma_f32 v195, -v245, v53, v195
	v_fmac_f32_e32 v196, v245, v21
	v_fmac_f32_e32 v152, v138, v22
	v_fmac_f32_e32 v153, v138, v54
	v_fma_f32 v152, -v246, v54, v152
	v_fmac_f32_e32 v153, v246, v22
	v_fmac_f32_e32 v195, v139, v23
	v_fmac_f32_e32 v196, v139, v55
	v_fma_f32 v195, -v247, v55, v195
	v_fmac_f32_e32 v196, v247, v23
	v_fmac_f32_e32 v152, v140, v24
	v_fmac_f32_e32 v153, v140, v56
	v_fma_f32 v152, -v248, v56, v152
	v_fmac_f32_e32 v153, v248, v24
	v_fmac_f32_e32 v195, v141, v25
	v_fmac_f32_e32 v196, v141, v57
	v_fma_f32 v195, -v249, v57, v195
	v_fmac_f32_e32 v196, v249, v25
	v_fmac_f32_e32 v152, v142, v26
	v_fmac_f32_e32 v153, v142, v58
	v_fma_f32 v152, -v250, v58, v152
	v_fmac_f32_e32 v153, v250, v26
	v_fmac_f32_e32 v195, v143, v27
	v_fmac_f32_e32 v196, v143, v59
	v_fma_f32 v195, -v251, v59, v195
	v_fmac_f32_e32 v196, v251, v27
	v_fmac_f32_e32 v152, v144, v28
	v_fmac_f32_e32 v153, v144, v60
	v_fma_f32 v152, -v252, v60, v152
	v_fmac_f32_e32 v153, v252, v28
	v_fmac_f32_e32 v195, v145, v29
	v_fmac_f32_e32 v196, v145, v61
	v_fma_f32 v195, -v253, v61, v195
	v_fmac_f32_e32 v196, v253, v29
	v_fmac_f32_e32 v152, v146, v30
	v_fmac_f32_e32 v153, v146, v62
	v_fma_f32 v152, -v210, v62, v152
	v_fmac_f32_e32 v153, v210, v30
	v_fmac_f32_e32 v195, v147, v31
	v_fmac_f32_e32 v196, v147, v63
	v_fma_f32 v195, -v211, v63, v195
	v_fmac_f32_e32 v196, v211, v31
	v_fmac_f32_e32 v152, v148, v32
	v_fmac_f32_e32 v153, v148, v64
	v_fma_f32 v152, -v212, v64, v152
	v_fmac_f32_e32 v153, v212, v32
	v_fmac_f32_e32 v195, v149, v33
	v_fmac_f32_e32 v196, v149, v65
	v_fma_f32 v195, -v213, v65, v195
	v_fmac_f32_e32 v196, v213, v33
	v_add_f32_e32 v152, v152, v195
	v_add_f32_e32 v153, v153, v196
	s_add_i32 s22, s22, -1
	s_cmp_lg_u32 s22, 0
	s_cbranch_scc1 .Lp1b_loop
	s_nop 1
	v_permlane32_swap_b32_e32 v150, v152
	v_permlane32_swap_b32_e32 v151, v153
	v_add_f32_e32 v111, v150, v152
	v_add_f32_e32 v110, v151, v153

; template <bool BWD, int MODE  >
; __device__ __forceinline__ void ssm_pass(const bf16* proj, int rowbase, int g, const bf16x8* BBp, const bf16x8* CCp, float ar, float ai, float& sr, float& si,
;                                          LAS unsigned* XS, int lane, f32x4* ysc, const float* Dp, bf16* zbuf) {
;     bf16x8 bb[4], cc[4];
; #pragma unroll
;     for (int t = 0; t < 4; ++t) { bb[t] = BBp[t * 64 + lane]; if (MODE > 0) cc[t] = CCp[t * 64 + lane]; }
;     const int ql = lane & 31, hi = lane >> 5;
;     const bf16* up = proj + (size_t)(rowbase + ql) * DIN + 768 + g * 16 + 8 * hi;
;     bf16x8 ucur = *(const bf16x8*)(up + (size_t)(BWD ? 15 : 0) * 32 * DIN);
;     float dval = 0.f; if (MODE == 2) dval = Dp[g * 16 + (lane & 15)];
;     for (int c = 0; c < 16; ++c) {
;         const int ch = BWD ? 15 - c : c;
;         bf16x8 unext = ucur;
;         if (c < 15) unext = *(const bf16x8*)(up + (size_t)(BWD ? ch - 1 : ch + 1) * 32 * DIN);
; __device__ __forceinline__ void ssm_p1(const Args& a, LAS unsigned char* lds, int layer, int G, int vb) {
;     ...
;         if (dir) ssm_pass<true, 0>(proj, rowbase, g, BBp, nullptr, ab[0], ab[1], sr, si, XS, lane, nullptr, nullptr, nullptr);
;         else     ssm_pass<false, 0>(proj, rowbase, g, BBp, nullptr, ab[0], ab[1], sr, si, XS, lane, nullptr, nullptr, nullptr);
.LBB0_444:
	s_and_b64 vcc, exec, s[22:23]
	s_cbranch_vccz .LBB0_437
	global_load_dwordx4 v[114:117], v[102:103], off
	v_lshl_add_u64 v[100:101], v[90:91], 0, v[100:101]
	s_mov_b64 s[78:79], 0x14000
	global_load_dwordx4 v[118:121], v[100:101], off
	v_lshl_add_u64 v[100:101], v[100:101], 0, s[78:79]
	global_load_dwordx4 v[122:125], v[100:101], off
	v_lshl_add_u64 v[100:101], v[100:101], 0, s[78:79]
	v_cmp_lt_u32_e32 vcc, 31, v86
	s_nop 1
	v_mul_f32_e32 v215, v98, v98
	v_fma_f32 v215, -v99, v99, v215
	v_mul_f32_e32 v216, v98, v99
	v_fmac_f32_e32 v216, v99, v98
	v_mul_f32_e32 v217, v215, v215
	v_fma_f32 v217, -v216, v216, v217
	v_mul_f32_e32 v194, v215, v216
	v_fmac_f32_e32 v194, v216, v215
	v_mul_f32_e32 v195, v217, v217
	v_fma_f32 v195, -v194, v194, v195
	v_mul_f32_e32 v196, v217, v194
	v_fmac_f32_e32 v196, v194, v217
	v_mul_f32_e32 v197, v195, v195
	v_fma_f32 v197, -v196, v196, v197
	v_mul_f32_e32 v198, v195, v196
	v_fmac_f32_e32 v198, v196, v195
	v_mul_f32_e32 v199, v197, v195
	v_fma_f32 v199, -v198, v196, v199
	v_mul_f32_e32 v200, v197, v196
	v_fmac_f32_e32 v200, v198, v195
	v_mul_f32_e32 v159, v197, v197
	v_fma_f32 v159, -v198, v198, v159
	v_mul_f32_e32 v160, v197, v198
	v_fmac_f32_e32 v160, v198, v197
	v_mov_b32_e32 v201, 1.0
	v_mov_b32_e32 v202, 0
	v_cndmask_b32_e32 v201, v217, v201, vcc
	v_cndmask_b32_e32 v202, v194, v202, vcc
	v_mul_f32_e32 v203, v201, v98
	v_fma_f32 v203, -v202, v99, v203
	v_mul_f32_e32 v204, v201, v99
	v_fmac_f32_e32 v204, v202, v98
	v_mul_f32_e32 v205, v201, v215
	v_fma_f32 v205, -v202, v216, v205
	v_mul_f32_e32 v206, v201, v216
	v_fmac_f32_e32 v206, v202, v215
	v_mul_f32_e32 v207, v205, v98
	v_fma_f32 v207, -v206, v99, v207
	v_mul_f32_e32 v208, v205, v99
	v_fmac_f32_e32 v208, v206, v98
	v_mul_f32_e32 v178, v207, v199
	v_fma_f32 v178, -v208, v200, v178
	v_mul_f32_e32 v226, v207, v200
	v_fmac_f32_e32 v226, v208, v199
	v_mul_f32_e32 v179, v205, v199
	v_fma_f32 v179, -v206, v200, v179
	v_mul_f32_e32 v227, v205, v200
	v_fmac_f32_e32 v227, v206, v199
	v_mul_f32_e32 v180, v203, v199
	v_fma_f32 v180, -v204, v200, v180
	v_mul_f32_e32 v228, v203, v200
	v_fmac_f32_e32 v228, v204, v199
	v_mul_f32_e32 v181, v201, v199
	v_fma_f32 v181, -v202, v200, v181
	v_mul_f32_e32 v229, v201, v200
	v_fmac_f32_e32 v229, v202, v199
	v_mul_f32_e32 v182, v207, v197
	v_fma_f32 v182, -v208, v198, v182
	v_mul_f32_e32 v230, v207, v198
	v_fmac_f32_e32 v230, v208, v197
	v_mul_f32_e32 v183, v205, v197
	v_fma_f32 v183, -v206, v198, v183
	v_mul_f32_e32 v231, v205, v198
	v_fmac_f32_e32 v231, v206, v197
	v_mul_f32_e32 v184, v203, v197
	v_fma_f32 v184, -v204, v198, v184
	v_mul_f32_e32 v232, v203, v198
	v_fmac_f32_e32 v232, v204, v197
	v_mul_f32_e32 v185, v201, v197
	v_fma_f32 v185, -v202, v198, v185
	v_mul_f32_e32 v233, v201, v198
	v_fmac_f32_e32 v233, v202, v197
	v_mul_f32_e32 v186, v207, v195
	v_fma_f32 v186, -v208, v196, v186
	v_mul_f32_e32 v234, v207, v196
	v_fmac_f32_e32 v234, v208, v195
	v_mul_f32_e32 v187, v205, v195
	v_fma_f32 v187, -v206, v196, v187
	v_mul_f32_e32 v235, v205, v196
	v_fmac_f32_e32 v235, v206, v195
	v_mul_f32_e32 v188, v203, v195
	v_fma_f32 v188, -v204, v196, v188
	v_mul_f32_e32 v236, v203, v196
	v_fmac_f32_e32 v236, v204, v195
	v_mul_f32_e32 v189, v201, v195
	v_fma_f32 v189, -v202, v196, v189
	v_mul_f32_e32 v237, v201, v196
	v_fmac_f32_e32 v237, v202, v195
	v_mov_b32_e32 v190, v207
	v_mov_b32_e32 v238, v208
	v_mov_b32_e32 v191, v205
	v_mov_b32_e32 v239, v206
	v_mov_b32_e32 v192, v203
	v_mov_b32_e32 v240, v204
	v_mov_b32_e32 v193, v201
	v_mov_b32_e32 v241, v202
	v_mul_f32_e32 v215, v130, v130
	v_fma_f32 v215, -v131, v131, v215
	v_mul_f32_e32 v216, v130, v131
	v_fmac_f32_e32 v216, v131, v130
	v_mul_f32_e32 v217, v215, v215
	v_fma_f32 v217, -v216, v216, v217
	v_mul_f32_e32 v194, v215, v216
	v_fmac_f32_e32 v194, v216, v215
	v_mul_f32_e32 v195, v217, v217
	v_fma_f32 v195, -v194, v194, v195
	v_mul_f32_e32 v196, v217, v194
	v_fmac_f32_e32 v196, v194, v217
	v_mul_f32_e32 v197, v195, v195
	v_fma_f32 v197, -v196, v196, v197
	v_mul_f32_e32 v198, v195, v196
	v_fmac_f32_e32 v198, v196, v195
	v_mul_f32_e32 v199, v197, v195
	v_fma_f32 v199, -v198, v196, v199
	v_mul_f32_e32 v200, v197, v196
	v_fmac_f32_e32 v200, v198, v195
	v_mul_f32_e32 v161, v197, v197
	v_fma_f32 v161, -v198, v198, v161
	v_mul_f32_e32 v214, v197, v198
	v_fmac_f32_e32 v214, v198, v197
	v_mov_b32_e32 v201, 1.0
	v_mov_b32_e32 v202, 0
	v_cndmask_b32_e32 v201, v217, v201, vcc
	v_cndmask_b32_e32 v202, v194, v202, vcc
	v_mul_f32_e32 v203, v201, v130
	v_fma_f32 v203, -v202, v131, v203
	v_mul_f32_e32 v204, v201, v131
	v_fmac_f32_e32 v204, v202, v130
	v_mul_f32_e32 v205, v201, v215
	v_fma_f32 v205, -v202, v216, v205
	v_mul_f32_e32 v206, v201, v216
	v_fmac_f32_e32 v206, v202, v215
	v_mul_f32_e32 v207, v205, v130
	v_fma_f32 v207, -v206, v131, v207
	v_mul_f32_e32 v208, v205, v131
	v_fmac_f32_e32 v208, v206, v130
	v_mul_f32_e32 v134, v207, v199
	v_fma_f32 v134, -v208, v200, v134
	v_mul_f32_e32 v242, v207, v200
	v_fmac_f32_e32 v242, v208, v199
	v_mul_f32_e32 v135, v205, v199
	v_fma_f32 v135, -v206, v200, v135
	v_mul_f32_e32 v243, v205, v200
	v_fmac_f32_e32 v243, v206, v199
	v_mul_f32_e32 v136, v203, v199
	v_fma_f32 v136, -v204, v200, v136
	v_mul_f32_e32 v244, v203, v200
	v_fmac_f32_e32 v244, v204, v199
	v_mul_f32_e32 v137, v201, v199
	v_fma_f32 v137, -v202, v200, v137
	v_mul_f32_e32 v245, v201, v200
	v_fmac_f32_e32 v245, v202, v199
	v_mul_f32_e32 v138, v207, v197
	v_fma_f32 v138, -v208, v198, v138
	v_mul_f32_e32 v246, v207, v198
	v_fmac_f32_e32 v246, v208, v197
	v_mul_f32_e32 v139, v205, v197
	v_fma_f32 v139, -v206, v198, v139
	v_mul_f32_e32 v247, v205, v198
	v_fmac_f32_e32 v247, v206, v197
	v_mul_f32_e32 v140, v203, v197
	v_fma_f32 v140, -v204, v198, v140
	v_mul_f32_e32 v248, v203, v198
	v_fmac_f32_e32 v248, v204, v197
	v_mul_f32_e32 v141, v201, v197
	v_fma_f32 v141, -v202, v198, v141
	v_mul_f32_e32 v249, v201, v198
	v_fmac_f32_e32 v249, v202, v197
	v_mul_f32_e32 v142, v207, v195
	v_fma_f32 v142, -v208, v196, v142
	v_mul_f32_e32 v250, v207, v196
	v_fmac_f32_e32 v250, v208, v195
	v_mul_f32_e32 v143, v205, v195
	v_fma_f32 v143, -v206, v196, v143
	v_mul_f32_e32 v251, v205, v196
	v_fmac_f32_e32 v251, v206, v195
	v_mul_f32_e32 v144, v203, v195
	v_fma_f32 v144, -v204, v196, v144
	v_mul_f32_e32 v252, v203, v196
	v_fmac_f32_e32 v252, v204, v195
	v_mul_f32_e32 v145, v201, v195
	v_fma_f32 v145, -v202, v196, v145
	v_mul_f32_e32 v253, v201, v196
	v_fmac_f32_e32 v253, v202, v195
	v_mov_b32_e32 v146, v207
	v_mov_b32_e32 v210, v208
	v_mov_b32_e32 v147, v205
	v_mov_b32_e32 v211, v206
	v_mov_b32_e32 v148, v203
	v_mov_b32_e32 v212, v204
	v_mov_b32_e32 v149, v201
	v_mov_b32_e32 v213, v202
	v_mov_b32_e32 v150, 0
	v_mov_b32_e32 v151, 0
	v_mov_b32_e32 v152, 0
	v_mov_b32_e32 v153, 0
	s_mov_b32 s22, 4
; __device__ __forceinline__ unsigned pk2(float lo, float hi) { const f32x2 v = {lo, hi}; return __builtin_bit_cast(unsigned, __builtin_convertvector(v, bf16x2_t)); }
; __device__ __forceinline__ float bflo(unsigned w) { return __uint_as_float(w << 16); }
; __device__ __forceinline__ float bfhi(unsigned w) { return __uint_as_float(w & 0xffff0000u); }
; #define LDS_FENCE() asm volatile("s_waitcnt lgkmcnt(0)" ::: "memory")
; __device__ __forceinline__ int crow(int r, int hi) { return (r & 3) + 8 * (r >> 2) + 4 * hi; }
; template <bool BWD, int MODE  >
; __device__ __forceinline__ void ssm_pass(const bf16* proj, int rowbase, int g, const bf16x8* BBp, const bf16x8* CCp, float ar, float ai, float& sr, float& si,
;                                          LAS unsigned* XS, int lane, f32x4* ysc, const float* Dp, bf16* zbuf) {
;     ...
;         const f32x16 x0 = __builtin_amdgcn_mfma_f32_32x32x16_bf16(ucur, bb[0], z16, 0, 0, 0);
;         const f32x16 x1 = __builtin_amdgcn_mfma_f32_32x32x16_bf16(ucur, bb[1], z16, 0, 0, 0);
;         const f32x16 x2 = __builtin_amdgcn_mfma_f32_32x32x16_bf16(ucur, bb[2], z16, 0, 0, 0);
;         const f32x16 x3 = __builtin_amdgcn_mfma_f32_32x32x16_bf16(ucur, bb[3], z16, 0, 0, 0);
; #pragma unroll
;         for (int r = 0; r < 16; ++r) { const int t = crow(r, hi); XS[t * XS_STRIDE + ql] = pk2(x0[r], x2[r]); XS[t * XS_STRIDE + 32 + ql] = pk2(x1[r], x3[r]); }
;         LDS_FENCE();
; #pragma unroll
;         for (int tt = 0; tt < 32; ++tt) {
;             const int t = BWD ? 31 - tt : tt;
;             const unsigned v = XS[t * XS_STRIDE + lane];
;             const float nr = fmaf(ar, sr, fmaf(-ai, si, bflo(v))), ni = fmaf(ar, si, fmaf(ai, sr, bfhi(v)));
;             sr = nr; si = ni;
;             if (MODE > 0) XS[t * XS_STRIDE + lane] = pk2(sr, si);
.Lp1f_loop:
	global_load_dwordx4 v[126:129], v[100:101], off
	v_lshl_add_u64 v[100:101], v[100:101], 0, s[78:79]
	s_waitcnt vmcnt(3)
	v_mfma_f32_32x32x16_bf16 v[2:17], v[114:117], v[74:77], 0
	v_mfma_f32_32x32x16_bf16 v[34:49], v[114:117], v[70:73], 0
	v_mfma_f32_32x32x16_bf16 v[18:33], v[114:117], v[66:69], 0
	v_mfma_f32_32x32x16_bf16 v[50:65], v[114:117], v[78:81], 0
	v_mul_f32_e32 v215, v160, v151
	v_mul_f32_e32 v216, v160, v150
	v_fma_f32 v150, v159, v150, -v215
	v_fma_f32 v151, v159, v151, v216
	v_mul_f32_e32 v215, v214, v153
	v_mul_f32_e32 v216, v214, v152
	v_fma_f32 v152, v161, v152, -v215
	v_fma_f32 v153, v161, v153, v216
	s_nop 3
	v_fmac_f32_e32 v150, v178, v2
	v_fmac_f32_e32 v151, v178, v34
	v_fma_f32 v150, -v226, v34, v150
	v_fmac_f32_e32 v151, v226, v2
	v_mul_f32_e32 v217, v179, v3
	v_mul_f32_e32 v194, v179, v35
	v_fma_f32 v217, -v227, v35, v217
	v_fmac_f32_e32 v194, v227, v3
	v_fmac_f32_e32 v150, v180, v4
	v_fmac_f32_e32 v151, v180, v36
	v_fma_f32 v150, -v228, v36, v150
	v_fmac_f32_e32 v151, v228, v4
	v_fmac_f32_e32 v217, v181, v5
	v_fmac_f32_e32 v194, v181, v37
	v_fma_f32 v217, -v229, v37, v217
	v_fmac_f32_e32 v194, v229, v5
	v_fmac_f32_e32 v150, v182, v6
	v_fmac_f32_e32 v151, v182, v38
	v_fma_f32 v150, -v230, v38, v150
	v_fmac_f32_e32 v151, v230, v6
	v_fmac_f32_e32 v217, v183, v7
	v_fmac_f32_e32 v194, v183, v39
	v_fma_f32 v217, -v231, v39, v217
	v_fmac_f32_e32 v194, v231, v7
	v_fmac_f32_e32 v150, v184, v8
	v_fmac_f32_e32 v151, v184, v40
	v_fma_f32 v150, -v232, v40, v150
	v_fmac_f32_e32 v151, v232, v8
	v_fmac_f32_e32 v217, v185, v9
	v_fmac_f32_e32 v194, v185, v41
	v_fma_f32 v217, -v233, v41, v217
	v_fmac_f32_e32 v194, v233, v9
	v_fmac_f32_e32 v150, v186, v10
	v_fmac_f32_e32 v151, v186, v42
	v_fma_f32 v150, -v234, v42, v150
	v_fmac_f32_e32 v151, v234, v10
	v_fmac_f32_e32 v217, v187, v11
	v_fmac_f32_e32 v194, v187, v43
	v_fma_f32 v217, -v235, v43, v217
	v_fmac_f32_e32 v194, v235, v11
	v_fmac_f32_e32 v150, v188, v12
	v_fmac_f32_e32 v151, v188, v44
	v_fma_f32 v150, -v236, v44, v150
	v_fmac_f32_e32 v151, v236, v12
	v_fmac_f32_e32 v217, v189, v13
	v_fmac_f32_e32 v194, v189, v45
	v_fma_f32 v217, -v237, v45, v217
	v_fmac_f32_e32 v194, v237, v13
	v_fmac_f32_e32 v150, v190, v14
	v_fmac_f32_e32 v151, v190, v46
	v_fma_f32 v150, -v238, v46, v150
	v_fmac_f32_e32 v151, v238, v14
	v_fmac_f32_e32 v217, v191, v15
	v_fmac_f32_e32 v194, v191, v47
	v_fma_f32 v217, -v239, v47, v217
	v_fmac_f32_e32 v194, v239, v15
	v_fmac_f32_e32 v150, v192, v16
	v_fmac_f32_e32 v151, v192, v48
	v_fma_f32 v150, -v240, v48, v150
	v_fmac_f32_e32 v151, v240, v16
	v_fmac_f32_e32 v217, v193, v17
	v_fmac_f32_e32 v194, v193, v49
	v_fma_f32 v217, -v241, v49, v217
	v_fmac_f32_e32 v194, v241, v17
	v_add_f32_e32 v150, v150, v217
	v_add_f32_e32 v151, v151, v194
	v_fmac_f32_e32 v152, v134, v18
	v_fmac_f32_e32 v153, v134, v50
	v_fma_f32 v152, -v242, v50, v152
	v_fmac_f32_e32 v153, v242, v18
	v_mul_f32_e32 v195, v135, v19
	v_mul_f32_e32 v196, v135, v51
	v_fma_f32 v195, -v243, v51, v195
	v_fmac_f32_e32 v196, v243, v19
	v_fmac_f32_e32 v152, v136, v20
	v_fmac_f32_e32 v153, v136, v52
	v_fma_f32 v152, -v244, v52, v152
	v_fmac_f32_e32 v153, v244, v20
	v_fmac_f32_e32 v195, v137, v21
	v_fmac_f32_e32 v196, v137, v53
	v_fma_f32 v195, -v245, v53, v195
	v_fmac_f32_e32 v196, v245, v21
	v_fmac_f32_e32 v152, v138, v22
	v_fmac_f32_e32 v153, v138, v54
	v_fma_f32 v152, -v246, v54, v152
	v_fmac_f32_e32 v153, v246, v22
	v_fmac_f32_e32 v195, v139, v23
	v_fmac_f32_e32 v196, v139, v55
	v_fma_f32 v195, -v247, v55, v195
	v_fmac_f32_e32 v196, v247, v23
	v_fmac_f32_e32 v152, v140, v24
	v_fmac_f32_e32 v153, v140, v56
	v_fma_f32 v152, -v248, v56, v152
	v_fmac_f32_e32 v153, v248, v24
	v_fmac_f32_e32 v195, v141, v25
	v_fmac_f32_e32 v196, v141, v57
	v_fma_f32 v195, -v249, v57, v195
	v_fmac_f32_e32 v196, v249, v25
	v_fmac_f32_e32 v152, v142, v26
	v_fmac_f32_e32 v153, v142, v58
	v_fma_f32 v152, -v250, v58, v152
	v_fmac_f32_e32 v153, v250, v26
	v_fmac_f32_e32 v195, v143, v27
	v_fmac_f32_e32 v196, v143, v59
	v_fma_f32 v195, -v251, v59, v195
	v_fmac_f32_e32 v196, v251, v27
	v_fmac_f32_e32 v152, v144, v28
	v_fmac_f32_e32 v153, v144, v60
	v_fma_f32 v152, -v252, v60, v152
	v_fmac_f32_e32 v153, v252, v28
	v_fmac_f32_e32 v195, v145, v29
	v_fmac_f32_e32 v196, v145, v61
	v_fma_f32 v195, -v253, v61, v195
	v_fmac_f32_e32 v196, v253, v29
	v_fmac_f32_e32 v152, v146, v30
	v_fmac_f32_e32 v153, v146, v62
	v_fma_f32 v152, -v210, v62, v152
	v_fmac_f32_e32 v153, v210, v30
	v_fmac_f32_e32 v195, v147, v31
	v_fmac_f32_e32 v196, v147, v63
	v_fma_f32 v195, -v211, v63, v195
	v_fmac_f32_e32 v196, v211, v31
	v_fmac_f32_e32 v152, v148, v32
	v_fmac_f32_e32 v153, v148, v64
	v_fma_f32 v152, -v212, v64, v152
	v_fmac_f32_e32 v153, v212, v32
	v_fmac_f32_e32 v195, v149, v33
	v_fmac_f32_e32 v196, v149, v65
	v_fma_f32 v195, -v213, v65, v195
	v_fmac_f32_e32 v196, v213, v33
	v_add_f32_e32 v152, v152, v195
	v_add_f32_e32 v153, v153, v196
	global_load_dwordx4 v[114:117], v[100:101], off
	v_lshl_add_u64 v[100:101], v[100:101], 0, s[78:79]
	s_waitcnt vmcnt(3)
; __device__ __forceinline__ unsigned pk2(float lo, float hi) { const f32x2 v = {lo, hi}; return __builtin_bit_cast(unsigned, __builtin_convertvector(v, bf16x2_t)); }
; __device__ __forceinline__ float bflo(unsigned w) { return __uint_as_float(w << 16); }
; __device__ __forceinline__ float bfhi(unsigned w) { return __uint_as_float(w & 0xffff0000u); }
; #define LDS_FENCE() asm volatile("s_waitcnt lgkmcnt(0)" ::: "memory")
; __device__ __forceinline__ int crow(int r, int hi) { return (r & 3) + 8 * (r >> 2) + 4 * hi; }
; template <bool BWD, int MODE  >
; __device__ __forceinline__ void ssm_pass(const bf16* proj, int rowbase, int g, const bf16x8* BBp, const bf16x8* CCp, float ar, float ai, float& sr, float& si,
;                                          LAS unsigned* XS, int lane, f32x4* ysc, const float* Dp, bf16* zbuf) {
;     ...
;         const f32x16 x0 = __builtin_amdgcn_mfma_f32_32x32x16_bf16(ucur, bb[0], z16, 0, 0, 0);
;         const f32x16 x1 = __builtin_amdgcn_mfma_f32_32x32x16_bf16(ucur, bb[1], z16, 0, 0, 0);
;         const f32x16 x2 = __builtin_amdgcn_mfma_f32_32x32x16_bf16(ucur, bb[2], z16, 0, 0, 0);
;         const f32x16 x3 = __builtin_amdgcn_mfma_f32_32x32x16_bf16(ucur, bb[3], z16, 0, 0, 0);
; #pragma unroll
;         for (int r = 0; r < 16; ++r) { const int t = crow(r, hi); XS[t * XS_STRIDE + ql] = pk2(x0[r], x2[r]); XS[t * XS_STRIDE + 32 + ql] = pk2(x1[r], x3[r]); }
;         LDS_FENCE();
; #pragma unroll
;         for (int tt = 0; tt < 32; ++tt) {
;             const int t = BWD ? 31 - tt : tt;
;             const unsigned v = XS[t * XS_STRIDE + lane];
;             const float nr = fmaf(ar, sr, fmaf(-ai, si, bflo(v))), ni = fmaf(ar, si, fmaf(ai, sr, bfhi(v)));
;             sr = nr; si = ni;
;             if (MODE > 0) XS[t * XS_STRIDE + lane] = pk2(sr, si);
	v_mfma_f32_32x32x16_bf16 v[2:17], v[118:121], v[74:77], 0
	v_mfma_f32_32x32x16_bf16 v[34:49], v[118:121], v[70:73], 0
	v_mfma_f32_32x32x16_bf16 v[18:33], v[118:121], v[66:69], 0
	v_mfma_f32_32x32x16_bf16 v[50:65], v[118:121], v[78:81], 0
	v_mul_f32_e32 v215, v160, v151
	v_mul_f32_e32 v216, v160, v150
	v_fma_f32 v150, v159, v150, -v215
	v_fma_f32 v151, v159, v151, v216
	v_mul_f32_e32 v215, v214, v153
	v_mul_f32_e32 v216, v214, v152
	v_fma_f32 v152, v161, v152, -v215
	v_fma_f32 v153, v161, v153, v216
	s_nop 3
	v_fmac_f32_e32 v150, v178, v2
	v_fmac_f32_e32 v151, v178, v34
	v_fma_f32 v150, -v226, v34, v150
	v_fmac_f32_e32 v151, v226, v2
	v_mul_f32_e32 v217, v179, v3
	v_mul_f32_e32 v194, v179, v35
	v_fma_f32 v217, -v227, v35, v217
	v_fmac_f32_e32 v194, v227, v3
	v_fmac_f32_e32 v150, v180, v4
	v_fmac_f32_e32 v151, v180, v36
	v_fma_f32 v150, -v228, v36, v150
	v_fmac_f32_e32 v151, v228, v4
	v_fmac_f32_e32 v217, v181, v5
	v_fmac_f32_e32 v194, v181, v37
	v_fma_f32 v217, -v229, v37, v217
	v_fmac_f32_e32 v194, v229, v5
	v_fmac_f32_e32 v150, v182, v6
	v_fmac_f32_e32 v151, v182, v38
	v_fma_f32 v150, -v230, v38, v150
	v_fmac_f32_e32 v151, v230, v6
	v_fmac_f32_e32 v217, v183, v7
	v_fmac_f32_e32 v194, v183, v39
	v_fma_f32 v217, -v231, v39, v217
	v_fmac_f32_e32 v194, v231, v7
	v_fmac_f32_e32 v150, v184, v8
	v_fmac_f32_e32 v151, v184, v40
	v_fma_f32 v150, -v232, v40, v150
	v_fmac_f32_e32 v151, v232, v8
	v_fmac_f32_e32 v217, v185, v9
	v_fmac_f32_e32 v194, v185, v41
	v_fma_f32 v217, -v233, v41, v217
	v_fmac_f32_e32 v194, v233, v9
	v_fmac_f32_e32 v150, v186, v10
	v_fmac_f32_e32 v151, v186, v42
	v_fma_f32 v150, -v234, v42, v150
	v_fmac_f32_e32 v151, v234, v10
	v_fmac_f32_e32 v217, v187, v11
	v_fmac_f32_e32 v194, v187, v43
	v_fma_f32 v217, -v235, v43, v217
	v_fmac_f32_e32 v194, v235, v11
	v_fmac_f32_e32 v150, v188, v12
	v_fmac_f32_e32 v151, v188, v44
	v_fma_f32 v150, -v236, v44, v150
	v_fmac_f32_e32 v151, v236, v12
	v_fmac_f32_e32 v217, v189, v13
	v_fmac_f32_e32 v194, v189, v45
	v_fma_f32 v217, -v237, v45, v217
	v_fmac_f32_e32 v194, v237, v13
	v_fmac_f32_e32 v150, v190, v14
	v_fmac_f32_e32 v151, v190, v46
	v_fma_f32 v150, -v238, v46, v150
	v_fmac_f32_e32 v151, v238, v14
	v_fmac_f32_e32 v217, v191, v15
	v_fmac_f32_e32 v194, v191, v47
	v_fma_f32 v217, -v239, v47, v217
	v_fmac_f32_e32 v194, v239, v15
	v_fmac_f32_e32 v150, v192, v16
	v_fmac_f32_e32 v151, v192, v48
	v_fma_f32 v150, -v240, v48, v150
	v_fmac_f32_e32 v151, v240, v16
	v_fmac_f32_e32 v217, v193, v17
	v_fmac_f32_e32 v194, v193, v49
	v_fma_f32 v217, -v241, v49, v217
	v_fmac_f32_e32 v194, v241, v17
	v_add_f32_e32 v150, v150, v217
	v_add_f32_e32 v151, v151, v194
	v_fmac_f32_e32 v152, v134, v18
	v_fmac_f32_e32 v153, v134, v50
	v_fma_f32 v152, -v242, v50, v152
	v_fmac_f32_e32 v153, v242, v18
	v_mul_f32_e32 v195, v135, v19
	v_mul_f32_e32 v196, v135, v51
	v_fma_f32 v195, -v243, v51, v195
	v_fmac_f32_e32 v196, v243, v19
	v_fmac_f32_e32 v152, v136, v20
	v_fmac_f32_e32 v153, v136, v52
	v_fma_f32 v152, -v244, v52, v152
	v_fmac_f32_e32 v153, v244, v20
	v_fmac_f32_e32 v195, v137, v21
	v_fmac_f32_e32 v196, v137, v53
	v_fma_f32 v195, -v245, v53, v195
	v_fmac_f32_e32 v196, v245, v21
	v_fmac_f32_e32 v152, v138, v22
	v_fmac_f32_e32 v153, v138, v54
	v_fma_f32 v152, -v246, v54, v152
	v_fmac_f32_e32 v153, v246, v22
	v_fmac_f32_e32 v195, v139, v23
	v_fmac_f32_e32 v196, v139, v55
	v_fma_f32 v195, -v247, v55, v195
	v_fmac_f32_e32 v196, v247, v23
	v_fmac_f32_e32 v152, v140, v24
	v_fmac_f32_e32 v153, v140, v56
	v_fma_f32 v152, -v248, v56, v152
	v_fmac_f32_e32 v153, v248, v24
	v_fmac_f32_e32 v195, v141, v25
	v_fmac_f32_e32 v196, v141, v57
	v_fma_f32 v195, -v249, v57, v195
	v_fmac_f32_e32 v196, v249, v25
	v_fmac_f32_e32 v152, v142, v26
	v_fmac_f32_e32 v153, v142, v58
	v_fma_f32 v152, -v250, v58, v152
	v_fmac_f32_e32 v153, v250, v26
	v_fmac_f32_e32 v195, v143, v27
	v_fmac_f32_e32 v196, v143, v59
	v_fma_f32 v195, -v251, v59, v195
	v_fmac_f32_e32 v196, v251, v27
	v_fmac_f32_e32 v152, v144, v28
	v_fmac_f32_e32 v153, v144, v60
	v_fma_f32 v152, -v252, v60, v152
	v_fmac_f32_e32 v153, v252, v28
	v_fmac_f32_e32 v195, v145, v29
	v_fmac_f32_e32 v196, v145, v61
	v_fma_f32 v195, -v253, v61, v195
	v_fmac_f32_e32 v196, v253, v29
	v_fmac_f32_e32 v152, v146, v30
	v_fmac_f32_e32 v153, v146, v62
	v_fma_f32 v152, -v210, v62, v152
	v_fmac_f32_e32 v153, v210, v30
	v_fmac_f32_e32 v195, v147, v31
	v_fmac_f32_e32 v196, v147, v63
	v_fma_f32 v195, -v211, v63, v195
	v_fmac_f32_e32 v196, v211, v31
	v_fmac_f32_e32 v152, v148, v32
	v_fmac_f32_e32 v153, v148, v64
	v_fma_f32 v152, -v212, v64, v152
	v_fmac_f32_e32 v153, v212, v32
	v_fmac_f32_e32 v195, v149, v33
	v_fmac_f32_e32 v196, v149, v65
	v_fma_f32 v195, -v213, v65, v195
	v_fmac_f32_e32 v196, v213, v33
	v_add_f32_e32 v152, v152, v195
	v_add_f32_e32 v153, v153, v196
	global_load_dwordx4 v[118:121], v[100:101], off
	v_lshl_add_u64 v[100:101], v[100:101], 0, s[78:79]
	s_waitcnt vmcnt(3)
; __device__ __forceinline__ unsigned pk2(float lo, float hi) { const f32x2 v = {lo, hi}; return __builtin_bit_cast(unsigned, __builtin_convertvector(v, bf16x2_t)); }
; __device__ __forceinline__ float bflo(unsigned w) { return __uint_as_float(w << 16); }
; __device__ __forceinline__ float bfhi(unsigned w) { return __uint_as_float(w & 0xffff0000u); }
; #define LDS_FENCE() asm volatile("s_waitcnt lgkmcnt(0)" ::: "memory")
; __device__ __forceinline__ int crow(int r, int hi) { return (r & 3) + 8 * (r >> 2) + 4 * hi; }
; template <bool BWD, int MODE  >
; __device__ __forceinline__ void ssm_pass(const bf16* proj, int rowbase, int g, const bf16x8* BBp, const bf16x8* CCp, float ar, float ai, float& sr, float& si,
;                                          LAS unsigned* XS, int lane, f32x4* ysc, const float* Dp, bf16* zbuf) {
;     ...
;         const f32x16 x0 = __builtin_amdgcn_mfma_f32_32x32x16_bf16(ucur, bb[0], z16, 0, 0, 0);
;         const f32x16 x1 = __builtin_amdgcn_mfma_f32_32x32x16_bf16(ucur, bb[1], z16, 0, 0, 0);
;         const f32x16 x2 = __builtin_amdgcn_mfma_f32_32x32x16_bf16(ucur, bb[2], z16, 0, 0, 0);
;         const f32x16 x3 = __builtin_amdgcn_mfma_f32_32x32x16_bf16(ucur, bb[3], z16, 0, 0, 0);
; #pragma unroll
;         for (int r = 0; r < 16; ++r) { const int t = crow(r, hi); XS[t * XS_STRIDE + ql] = pk2(x0[r], x2[r]); XS[t * XS_STRIDE + 32 + ql] = pk2(x1[r], x3[r]); }
;         LDS_FENCE();
; #pragma unroll
;         for (int tt = 0; tt < 32; ++tt) {
;             const int t = BWD ? 31 - tt : tt;
;             const unsigned v = XS[t * XS_STRIDE + lane];
;             const float nr = fmaf(ar, sr, fmaf(-ai, si, bflo(v))), ni = fmaf(ar, si, fmaf(ai, sr, bfhi(v)));
;             sr = nr; si = ni;
;             if (MODE > 0) XS[t * XS_STRIDE + lane] = pk2(sr, si);
	v_mfma_f32_32x32x16_bf16 v[2:17], v[122:125], v[74:77], 0
	v_mfma_f32_32x32x16_bf16 v[34:49], v[122:125], v[70:73], 0
	v_mfma_f32_32x32x16_bf16 v[18:33], v[122:125], v[66:69], 0
	v_mfma_f32_32x32x16_bf16 v[50:65], v[122:125], v[78:81], 0
	v_mul_f32_e32 v215, v160, v151
	v_mul_f32_e32 v216, v160, v150
	v_fma_f32 v150, v159, v150, -v215
	v_fma_f32 v151, v159, v151, v216
	v_mul_f32_e32 v215, v214, v153
	v_mul_f32_e32 v216, v214, v152
	v_fma_f32 v152, v161, v152, -v215
	v_fma_f32 v153, v161, v153, v216
	s_nop 3
	v_fmac_f32_e32 v150, v178, v2
	v_fmac_f32_e32 v151, v178, v34
	v_fma_f32 v150, -v226, v34, v150
	v_fmac_f32_e32 v151, v226, v2
	v_mul_f32_e32 v217, v179, v3
	v_mul_f32_e32 v194, v179, v35
	v_fma_f32 v217, -v227, v35, v217
	v_fmac_f32_e32 v194, v227, v3
	v_fmac_f32_e32 v150, v180, v4
	v_fmac_f32_e32 v151, v180, v36
	v_fma_f32 v150, -v228, v36, v150
	v_fmac_f32_e32 v151, v228, v4
	v_fmac_f32_e32 v217, v181, v5
	v_fmac_f32_e32 v194, v181, v37
	v_fma_f32 v217, -v229, v37, v217
	v_fmac_f32_e32 v194, v229, v5
	v_fmac_f32_e32 v150, v182, v6
	v_fmac_f32_e32 v151, v182, v38
	v_fma_f32 v150, -v230, v38, v150
	v_fmac_f32_e32 v151, v230, v6
	v_fmac_f32_e32 v217, v183, v7
	v_fmac_f32_e32 v194, v183, v39
	v_fma_f32 v217, -v231, v39, v217
	v_fmac_f32_e32 v194, v231, v7
	v_fmac_f32_e32 v150, v184, v8
	v_fmac_f32_e32 v151, v184, v40
	v_fma_f32 v150, -v232, v40, v150
	v_fmac_f32_e32 v151, v232, v8
	v_fmac_f32_e32 v217, v185, v9
	v_fmac_f32_e32 v194, v185, v41
	v_fma_f32 v217, -v233, v41, v217
	v_fmac_f32_e32 v194, v233, v9
	v_fmac_f32_e32 v150, v186, v10
	v_fmac_f32_e32 v151, v186, v42
	v_fma_f32 v150, -v234, v42, v150
	v_fmac_f32_e32 v151, v234, v10
	v_fmac_f32_e32 v217, v187, v11
	v_fmac_f32_e32 v194, v187, v43
	v_fma_f32 v217, -v235, v43, v217
	v_fmac_f32_e32 v194, v235, v11
	v_fmac_f32_e32 v150, v188, v12
	v_fmac_f32_e32 v151, v188, v44
	v_fma_f32 v150, -v236, v44, v150
	v_fmac_f32_e32 v151, v236, v12
	v_fmac_f32_e32 v217, v189, v13
	v_fmac_f32_e32 v194, v189, v45
	v_fma_f32 v217, -v237, v45, v217
	v_fmac_f32_e32 v194, v237, v13
	v_fmac_f32_e32 v150, v190, v14
	v_fmac_f32_e32 v151, v190, v46
	v_fma_f32 v150, -v238, v46, v150
	v_fmac_f32_e32 v151, v238, v14
	v_fmac_f32_e32 v217, v191, v15
	v_fmac_f32_e32 v194, v191, v47
	v_fma_f32 v217, -v239, v47, v217
	v_fmac_f32_e32 v194, v239, v15
	v_fmac_f32_e32 v150, v192, v16
	v_fmac_f32_e32 v151, v192, v48
	v_fma_f32 v150, -v240, v48, v150
	v_fmac_f32_e32 v151, v240, v16
	v_fmac_f32_e32 v217, v193, v17
	v_fmac_f32_e32 v194, v193, v49
	v_fma_f32 v217, -v241, v49, v217
	v_fmac_f32_e32 v194, v241, v17
	v_add_f32_e32 v150, v150, v217
	v_add_f32_e32 v151, v151, v194
	v_fmac_f32_e32 v152, v134, v18
	v_fmac_f32_e32 v153, v134, v50
	v_fma_f32 v152, -v242, v50, v152
	v_fmac_f32_e32 v153, v242, v18
	v_mul_f32_e32 v195, v135, v19
	v_mul_f32_e32 v196, v135, v51
	v_fma_f32 v195, -v243, v51, v195
	v_fmac_f32_e32 v196, v243, v19
	v_fmac_f32_e32 v152, v136, v20
	v_fmac_f32_e32 v153, v136, v52
	v_fma_f32 v152, -v244, v52, v152
	v_fmac_f32_e32 v153, v244, v20
	v_fmac_f32_e32 v195, v137, v21
	v_fmac_f32_e32 v196, v137, v53
	v_fma_f32 v195, -v245, v53, v195
	v_fmac_f32_e32 v196, v245, v21
	v_fmac_f32_e32 v152, v138, v22
	v_fmac_f32_e32 v153, v138, v54
	v_fma_f32 v152, -v246, v54, v152
	v_fmac_f32_e32 v153, v246, v22
	v_fmac_f32_e32 v195, v139, v23
	v_fmac_f32_e32 v196, v139, v55
	v_fma_f32 v195, -v247, v55, v195
	v_fmac_f32_e32 v196, v247, v23
	v_fmac_f32_e32 v152, v140, v24
	v_fmac_f32_e32 v153, v140, v56
	v_fma_f32 v152, -v248, v56, v152
	v_fmac_f32_e32 v153, v248, v24
	v_fmac_f32_e32 v195, v141, v25
	v_fmac_f32_e32 v196, v141, v57
	v_fma_f32 v195, -v249, v57, v195
	v_fmac_f32_e32 v196, v249, v25
	v_fmac_f32_e32 v152, v142, v26
	v_fmac_f32_e32 v153, v142, v58
	v_fma_f32 v152, -v250, v58, v152
	v_fmac_f32_e32 v153, v250, v26
	v_fmac_f32_e32 v195, v143, v27
	v_fmac_f32_e32 v196, v143, v59
	v_fma_f32 v195, -v251, v59, v195
	v_fmac_f32_e32 v196, v251, v27
	v_fmac_f32_e32 v152, v144, v28
	v_fmac_f32_e32 v153, v144, v60
	v_fma_f32 v152, -v252, v60, v152
	v_fmac_f32_e32 v153, v252, v28
	v_fmac_f32_e32 v195, v145, v29
	v_fmac_f32_e32 v196, v145, v61
	v_fma_f32 v195, -v253, v61, v195
	v_fmac_f32_e32 v196, v253, v29
	v_fmac_f32_e32 v152, v146, v30
	v_fmac_f32_e32 v153, v146, v62
	v_fma_f32 v152, -v210, v62, v152
	v_fmac_f32_e32 v153, v210, v30
	v_fmac_f32_e32 v195, v147, v31
	v_fmac_f32_e32 v196, v147, v63
	v_fma_f32 v195, -v211, v63, v195
	v_fmac_f32_e32 v196, v211, v31
	v_fmac_f32_e32 v152, v148, v32
	v_fmac_f32_e32 v153, v148, v64
	v_fma_f32 v152, -v212, v64, v152
	v_fmac_f32_e32 v153, v212, v32
	v_fmac_f32_e32 v195, v149, v33
	v_fmac_f32_e32 v196, v149, v65
	v_fma_f32 v195, -v213, v65, v195
	v_fmac_f32_e32 v196, v213, v33
	v_add_f32_e32 v152, v152, v195
	v_add_f32_e32 v153, v153, v196
	global_load_dwordx4 v[122:125], v[100:101], off
	v_lshl_add_u64 v[100:101], v[100:101], 0, s[78:79]
	s_waitcnt vmcnt(3)
; __device__ __forceinline__ unsigned pk2(float lo, float hi) { const f32x2 v = {lo, hi}; return __builtin_bit_cast(unsigned, __builtin_convertvector(v, bf16x2_t)); }
; __device__ __forceinline__ float bflo(unsigned w) { return __uint_as_float(w << 16); }
; __device__ __forceinline__ float bfhi(unsigned w) { return __uint_as_float(w & 0xffff0000u); }
; #define LDS_FENCE() asm volatile("s_waitcnt lgkmcnt(0)" ::: "memory")
; __device__ __forceinline__ int crow(int r, int hi) { return (r & 3) + 8 * (r >> 2) + 4 * hi; }
; template <bool BWD, int MODE  >
; __device__ __forceinline__ void ssm_pass(const bf16* proj, int rowbase, int g, const bf16x8* BBp, const bf16x8* CCp, float ar, float ai, float& sr, float& si,
;                                          LAS unsigned* XS, int lane, f32x4* ysc, const float* Dp, bf16* zbuf) {
;     ...
;         const f32x16 x0 = __builtin_amdgcn_mfma_f32_32x32x16_bf16(ucur, bb[0], z16, 0, 0, 0);
;         const f32x16 x1 = __builtin_amdgcn_mfma_f32_32x32x16_bf16(ucur, bb[1], z16, 0, 0, 0);
;         const f32x16 x2 = __builtin_amdgcn_mfma_f32_32x32x16_bf16(ucur, bb[2], z16, 0, 0, 0);
;         const f32x16 x3 = __builtin_amdgcn_mfma_f32_32x32x16_bf16(ucur, bb[3], z16, 0, 0, 0);
; #pragma unroll
;         for (int r = 0; r < 16; ++r) { const int t = crow(r, hi); XS[t * XS_STRIDE + ql] = pk2(x0[r], x2[r]); XS[t * XS_STRIDE + 32 + ql] = pk2(x1[r], x3[r]); }
;         LDS_FENCE();
; #pragma unroll
;         for (int tt = 0; tt < 32; ++tt) {
;             const int t = BWD ? 31 - tt : tt;
;             const unsigned v = XS[t * XS_STRIDE + lane];
;             const float nr = fmaf(ar, sr, fmaf(-ai, si, bflo(v))), ni = fmaf(ar, si, fmaf(ai, sr, bfhi(v)));
;             sr = nr; si = ni;
;             if (MODE > 0) XS[t * XS_STRIDE + lane] = pk2(sr, si);
; __device__ __forceinline__ void ssm_p1(const Args& a, LAS unsigned char* lds, int layer, int G, int vb) {
;     ...
;         if (dir) ssm_pass<true, 0>(proj, rowbase, g, BBp, nullptr, ab[0], ab[1], sr, si, XS, lane, nullptr, nullptr, nullptr);
;         else     ssm_pass<false, 0>(proj, rowbase, g, BBp, nullptr, ab[0], ab[1], sr, si, XS, lane, nullptr, nullptr, nullptr);
;         SE[((size_t)((b * 32 + g) * 2 + dir) * 8 + seg) * 64 + lane] = (f32x2){sr, si};
	v_mfma_f32_32x32x16_bf16 v[2:17], v[126:129], v[74:77], 0
	v_mfma_f32_32x32x16_bf16 v[34:49], v[126:129], v[70:73], 0
	v_mfma_f32_32x32x16_bf16 v[18:33], v[126:129], v[66:69], 0
	v_mfma_f32_32x32x16_bf16 v[50:65], v[126:129], v[78:81], 0
	v_mul_f32_e32 v215, v160, v151
	v_mul_f32_e32 v216, v160, v150
	v_fma_f32 v150, v159, v150, -v215
	v_fma_f32 v151, v159, v151, v216
	v_mul_f32_e32 v215, v214, v153
	v_mul_f32_e32 v216, v214, v152
	v_fma_f32 v152, v161, v152, -v215
	v_fma_f32 v153, v161, v153, v216
	s_nop 3
	v_fmac_f32_e32 v150, v178, v2
	v_fmac_f32_e32 v151, v178, v34
	v_fma_f32 v150, -v226, v34, v150
	v_fmac_f32_e32 v151, v226, v2
	v_mul_f32_e32 v217, v179, v3
	v_mul_f32_e32 v194, v179, v35
	v_fma_f32 v217, -v227, v35, v217
	v_fmac_f32_e32 v194, v227, v3
	v_fmac_f32_e32 v150, v180, v4
	v_fmac_f32_e32 v151, v180, v36
	v_fma_f32 v150, -v228, v36, v150
	v_fmac_f32_e32 v151, v228, v4
	v_fmac_f32_e32 v217, v181, v5
	v_fmac_f32_e32 v194, v181, v37
	v_fma_f32 v217, -v229, v37, v217
	v_fmac_f32_e32 v194, v229, v5
	v_fmac_f32_e32 v150, v182, v6
	v_fmac_f32_e32 v151, v182, v38
	v_fma_f32 v150, -v230, v38, v150
	v_fmac_f32_e32 v151, v230, v6
	v_fmac_f32_e32 v217, v183, v7
	v_fmac_f32_e32 v194, v183, v39
	v_fma_f32 v217, -v231, v39, v217
	v_fmac_f32_e32 v194, v231, v7
	v_fmac_f32_e32 v150, v184, v8
	v_fmac_f32_e32 v151, v184, v40
	v_fma_f32 v150, -v232, v40, v150
	v_fmac_f32_e32 v151, v232, v8
	v_fmac_f32_e32 v217, v185, v9
	v_fmac_f32_e32 v194, v185, v41
	v_fma_f32 v217, -v233, v41, v217
	v_fmac_f32_e32 v194, v233, v9
	v_fmac_f32_e32 v150, v186, v10
	v_fmac_f32_e32 v151, v186, v42
	v_fma_f32 v150, -v234, v42, v150
	v_fmac_f32_e32 v151, v234, v10
	v_fmac_f32_e32 v217, v187, v11
	v_fmac_f32_e32 v194, v187, v43
	v_fma_f32 v217, -v235, v43, v217
	v_fmac_f32_e32 v194, v235, v11
	v_fmac_f32_e32 v150, v188, v12
	v_fmac_f32_e32 v151, v188, v44
	v_fma_f32 v150, -v236, v44, v150
	v_fmac_f32_e32 v151, v236, v12
	v_fmac_f32_e32 v217, v189, v13
	v_fmac_f32_e32 v194, v189, v45
	v_fma_f32 v217, -v237, v45, v217
	v_fmac_f32_e32 v194, v237, v13
	v_fmac_f32_e32 v150, v190, v14
	v_fmac_f32_e32 v151, v190, v46
	v_fma_f32 v150, -v238, v46, v150
	v_fmac_f32_e32 v151, v238, v14
	v_fmac_f32_e32 v217, v191, v15
	v_fmac_f32_e32 v194, v191, v47
	v_fma_f32 v217, -v239, v47, v217
	v_fmac_f32_e32 v194, v239, v15
	v_fmac_f32_e32 v150, v192, v16
	v_fmac_f32_e32 v151, v192, v48
	v_fma_f32 v150, -v240, v48, v150
	v_fmac_f32_e32 v151, v240, v16
	v_fmac_f32_e32 v217, v193, v17
	v_fmac_f32_e32 v194, v193, v49
	v_fma_f32 v217, -v241, v49, v217
	v_fmac_f32_e32 v194, v241, v17
	v_add_f32_e32 v150, v150, v217
	v_add_f32_e32 v151, v151, v194
	v_fmac_f32_e32 v152, v134, v18
	v_fmac_f32_e32 v153, v134, v50
	v_fma_f32 v152, -v242, v50, v152
	v_fmac_f32_e32 v153, v242, v18
	v_mul_f32_e32 v195, v135, v19
	v_mul_f32_e32 v196, v135, v51
	v_fma_f32 v195, -v243, v51, v195
	v_fmac_f32_e32 v196, v243, v19
	v_fmac_f32_e32 v152, v136, v20
	v_fmac_f32_e32 v153, v136, v52
	v_fma_f32 v152, -v244, v52, v152
	v_fmac_f32_e32 v153, v244, v20
	v_fmac_f32_e32 v195, v137, v21
	v_fmac_f32_e32 v196, v137, v53
	v_fma_f32 v195, -v245, v53, v195
	v_fmac_f32_e32 v196, v245, v21
	v_fmac_f32_e32 v152, v138, v22
	v_fmac_f32_e32 v153, v138, v54
	v_fma_f32 v152, -v246, v54, v152
	v_fmac_f32_e32 v153, v246, v22
	v_fmac_f32_e32 v195, v139, v23
	v_fmac_f32_e32 v196, v139, v55
	v_fma_f32 v195, -v247, v55, v195
	v_fmac_f32_e32 v196, v247, v23
	v_fmac_f32_e32 v152, v140, v24
	v_fmac_f32_e32 v153, v140, v56
	v_fma_f32 v152, -v248, v56, v152
	v_fmac_f32_e32 v153, v248, v24
	v_fmac_f32_e32 v195, v141, v25
	v_fmac_f32_e32 v196, v141, v57
	v_fma_f32 v195, -v249, v57, v195
	v_fmac_f32_e32 v196, v249, v25
	v_fmac_f32_e32 v152, v142, v26
	v_fmac_f32_e32 v153, v142, v58
	v_fma_f32 v152, -v250, v58, v152
	v_fmac_f32_e32 v153, v250, v26
	v_fmac_f32_e32 v195, v143, v27
	v_fmac_f32_e32 v196, v143, v59
	v_fma_f32 v195, -v251, v59, v195
	v_fmac_f32_e32 v196, v251, v27
	v_fmac_f32_e32 v152, v144, v28
	v_fmac_f32_e32 v153, v144, v60
	v_fma_f32 v152, -v252, v60, v152
	v_fmac_f32_e32 v153, v252, v28
	v_fmac_f32_e32 v195, v145, v29
	v_fmac_f32_e32 v196, v145, v61
	v_fma_f32 v195, -v253, v61, v195
	v_fmac_f32_e32 v196, v253, v29
	v_fmac_f32_e32 v152, v146, v30
	v_fmac_f32_e32 v153, v146, v62
	v_fma_f32 v152, -v210, v62, v152
	v_fmac_f32_e32 v153, v210, v30
	v_fmac_f32_e32 v195, v147, v31
	v_fmac_f32_e32 v196, v147, v63
	v_fma_f32 v195, -v211, v63, v195
	v_fmac_f32_e32 v196, v211, v31
	v_fmac_f32_e32 v152, v148, v32
	v_fmac_f32_e32 v153, v148, v64
	v_fma_f32 v152, -v212, v64, v152
	v_fmac_f32_e32 v153, v212, v32
	v_fmac_f32_e32 v195, v149, v33
	v_fmac_f32_e32 v196, v149, v65
	v_fma_f32 v195, -v213, v65, v195
	v_fmac_f32_e32 v196, v213, v33
	v_add_f32_e32 v152, v152, v195
	v_add_f32_e32 v153, v153, v196
	s_add_i32 s22, s22, -1
	s_cmp_lg_u32 s22, 0
	s_cbranch_scc1 .Lp1f_loop
	s_nop 1
	v_permlane32_swap_b32_e32 v150, v152
	v_permlane32_swap_b32_e32 v151, v153
	v_add_f32_e32 v111, v150, v152
	v_add_f32_e32 v110, v151, v153
	s_branch .LBB0_437
